# first K iteration of each unit (P1/P4/P5): phase A/B waits count the previous epilogue's stores as in flight instead of draining them; on top of packed P4 epilogue
# baseline (speedup 1.0000x reference)
;     __host__ __device__ bool next(int i_, Unit& u) const {
;         int i = i_; if (sh) { const int nr = (nwg - c + G - 1) / G; if (i >= 2 * nr) return false; if (i >= nr) i -= nr; }
;         const long L = (long)i * G + c; if (L >= nwg) return false;
;         int wgid = (int)L; { const int q = nwg / NXCD, r = nwg % NXCD, xcd = wgid % NXCD, off = wgid / NXCD; wgid = (xcd < r ? xcd * (q + 1) : r * (q + 1) + (xcd - r) * q) + off; }
; template <class Epi, class Sched, bool ALIGN_EPI = false, bool SP2 = false, bool ABLK = false>
; __device__ __forceinline__ void gemm_phase(PG8_LAS unsigned char* lds, const Gemm g, const Sched& S, const Epi& E) {
;     ...
;     const int tid = tid_, wid = __builtin_amdgcn_readfirstlane(tid >> 6), lane = tid & 63, wr = wid >> 2, wc = wid & 3, fr = lane & 15, fq = lane >> 4;
;     const int K = g.K, nt = K / BK;
;     unsigned voffA[2], voffB[2];
; #pragma unroll
;     for (int i = 0; i < 2; ++i) { int R, C; stage_rc(tid * 16 + i * 8192, R, C); const int Rb = Epi::PERM ? ((R & ~31) + perm32(R & 31)) : R;
;         voffA[i] = (unsigned)(R * (ABLK ? BK : K) + C) * 2u; voffB[i] = (unsigned)(Rb * K + C) * 2u; }
;     const size_t kstep = (size_t)(BK * 2);
;     const size_t hstep = (size_t)HALF * K * 2;
;     const size_t tstep = 2 * hstep;
;     const size_t kstepA = ABLK ? (size_t)(BM * BK * 2) : kstep, hstepA = ABLK ? (size_t)(HALF * BK * 2) : hstep, tstepA = ABLK ? (size_t)nt * (BM * BK * 2) : tstep;
;     const unsigned ldsw = (unsigned)wid * 1024u;
;     const int aoff = lds_byte(wr * 64 + fr, fq * 8), boff = lds_byte(wc * 32 + fr, fq * 8);
;     ...
;     Unit cur, nxt; int ui = 0;
;     if (!S.next(0, cur)) return;
;     f32x4 acc[2][2][4][2];
; #pragma unroll
;     for (int a = 0; a < 2; ++a)
; #pragma unroll
;         for (int b = 0; b < 2; ++b)
; #pragma unroll
;             for (int m = 0; m < 4; ++m)
; #pragma unroll
;                 for (int n = 0; n < 2; ++n) acc[a][b][m][n] = (f32x4){0.f, 0.f, 0.f, 0.f};
;     bf16x8 At[4][2], B0[2][2], B1[2][2];
;     const char* cA = (const char*)g.A + (size_t)cur.pm * tstepA; const char* cB = (const char*)g.Bt + (size_t)cur.pn * tstep;
;     S.a_ready(cur);
;     if constexpr (SP2) {
;         PG8_STAGE(PG8_SB(0, 0), cB, voffB); PG8_STAGE(PG8_SB(0, 1), cB + hstep, voffB); PG8_STAGE(PG8_SA(0, 0), cA, voffA); PG8_STAGE(PG8_SA(0, 1), cA + hstepA, voffA);
;         if (wr == 1) PG8_BAR;
.LBB0_206:
	s_mov_b32 s101, 0
	s_add_u32 s62, s70, 0x16000000
	s_addc_u32 s63, s71, 0
	v_mov_b32_e32 v9, v175
	s_cmpk_lt_i32 s2, 0x480
	v_readfirstlane_b32 s5, v9
	s_cbranch_scc0 .LBB0_226
	v_lshlrev_b32_e32 v0, 4, v9
	v_add_u32_e32 v1, 0x2000, v0
	v_ashrrev_i32_e32 v2, 31, v1
	v_lshrrev_b32_e32 v2, 22, v2
	v_add_u32_e32 v2, v1, v2
	v_ashrrev_i32_e32 v8, 10, v2
	v_mul_i32_i24_e32 v2, 0x400, v8
	v_sub_u32_e32 v1, v1, v2
	v_lshrrev_b32_e32 v2, 4, v1
	v_bitop3_b32 v1, v2, v1, 32 bitop3:0x6c
	v_ashrrev_i32_e32 v2, 31, v1
	v_lshrrev_b32_e32 v2, 26, v2
	v_add_u32_e32 v2, v1, v2
	v_lshlrev_b32_e32 v3, 3, v8
	v_ashrrev_i32_e32 v10, 6, v2
	v_and_b32_e32 v3, -16, v3
	v_add_u32_e32 v3, v10, v3
	v_and_b32_e32 v4, 3, v10
	s_mov_b32 s0, 0x1fffe0
	v_lshrrev_b32_e32 v5, 2, v3
	v_lshlrev_b32_e32 v6, 1, v3
	v_and_b32_e32 v2, 0xc0, v2
	v_and_or_b32 v4, v3, s0, v4
	v_and_b32_e32 v5, 4, v5
	v_and_b32_e32 v6, 24, v6
	v_sub_u32_e32 v1, v1, v2
	v_mov_b32_e32 v2, 1
	v_or3_b32 v4, v4, v5, v6
	v_lshlrev_b32_e32 v5, 5, v8
	v_ashrrev_i16_sdwa v1, v2, sext(v1) dst_sel:DWORD dst_unused:UNUSED_PAD src0_sel:DWORD src1_sel:BYTE_0
	v_and_b32_e32 v5, 32, v5
	v_bfe_i32 v11, v1, 0, 16
	v_add_lshl_u32 v1, v5, v11, 1
	v_lshl_add_u32 v132, v4, 11, v1
	v_lshl_add_u32 v134, v3, 11, v1
	v_bfe_i32 v1, v9, 27, 1
	v_lshrrev_b32_e32 v1, 22, v1
	v_add_u32_e32 v1, v0, v1
	v_and_b32_e32 v1, 0xfffffc00, v1
	v_sub_u32_e32 v0, v0, v1
	v_lshrrev_b32_e32 v1, 4, v0
	v_ashrrev_i32_e32 v3, 31, v9
	v_bitop3_b32 v0, v1, v0, 32 bitop3:0x6c
	v_lshrrev_b32_e32 v3, 26, v3
	v_ashrrev_i32_e32 v1, 31, v0
	v_add_u32_e32 v3, v9, v3
	v_lshrrev_b32_e32 v1, 26, v1
	v_ashrrev_i32_e32 v13, 6, v3
	v_add_u32_e32 v1, v0, v1
	v_lshlrev_b32_e32 v3, 3, v13
	v_ashrrev_i32_e32 v12, 6, v1
	v_and_b32_e32 v3, -16, v3
	v_add_u32_e32 v3, v12, v3
	v_and_b32_e32 v4, 3, v12
	s_ashr_i32 s47, s2, 31
	v_and_or_b32 v4, v3, s0, v4
	s_lshr_b32 s0, s47, 29
	s_add_i32 s0, s2, s0
	s_ashr_i32 s7, s5, 6
	s_ashr_i32 s1, s0, 3
	s_and_b32 s0, s0, -8
	s_ashr_i32 s6, s5, 8
	s_lshl_b32 s46, s7, 10
	s_sub_i32 s0, s2, s0
	s_cmp_lt_i32 s0, 0
	s_movk_i32 s69, 0x91
	s_cselect_b32 s4, s69, 0x90
	s_mul_i32 s0, s0, s4
	s_add_i32 s0, s0, s1
	s_mul_hi_i32 s1, s0, 0x38e38e39
	s_lshr_b32 s4, s1, 31
	s_ashr_i32 s1, s1, 4
	s_add_i32 s1, s1, s4
	s_lshl_b32 s8, s1, 3
	s_mulk_i32 s1, 0x48
	s_sub_i32 s0, s0, s1
	s_bfe_i32 s1, s0, 0x80000
	s_bfe_u32 s1, s1, 0x3000c
	s_add_i32 s1, s0, s1
	s_bfe_i32 s4, s1, 0x80000
	s_and_b32 s1, s1, 0xf8
	s_sub_i32 s0, s0, s1
	s_sext_i32_i16 s4, s4
	s_sext_i32_i8 s0, s0
	v_lshrrev_b32_e32 v5, 2, v3
	v_lshlrev_b32_e32 v6, 1, v3
	v_and_b32_e32 v1, 0xc0, v1
	s_lshr_b32 s4, s4, 3
	s_add_i32 s96, s8, s0
	v_and_b32_e32 v5, 4, v5
	v_and_b32_e32 v6, 24, v6
	v_sub_u32_e32 v0, v0, v1
	s_ashr_i32 s97, s96, 31
	s_bfe_i64 s[0:1], s[4:5], 0x100000
	v_or3_b32 v4, v4, v5, v6
	v_lshlrev_b32_e32 v5, 5, v13
	v_ashrrev_i16_sdwa v0, v2, sext(v0) dst_sel:DWORD dst_unused:UNUSED_PAD src0_sel:DWORD src1_sel:BYTE_0
	s_lshl_b64 s[8:9], s[96:97], 19
	s_lshl_b64 s[0:1], s[0:1], 19
	v_and_b32_e32 v5, 32, v5
	v_bfe_i32 v14, v0, 0, 16
	s_add_u32 s0, s74, s0
	v_add_lshl_u32 v0, v5, v14, 1
	s_addc_u32 s1, s75, s1
	s_add_i32 s97, s46, 0
	v_lshl_add_u32 v136, v4, 11, v0
	s_add_i32 m0, s97, 0x10000
	v_lshl_add_u32 v138, v3, 11, v0
	global_load_lds_dwordx4 v136, s[0:1]
	s_add_i32 m0, s97, 0x12000
	s_add_u32 s10, s0, 0x40000
	global_load_lds_dwordx4 v132, s[0:1]
	s_addc_u32 s11, s1, 0
	s_add_i32 m0, s97, 0x14000
	v_writelane_b32 v244, s94, 24
	global_load_lds_dwordx4 v136, s[10:11]
	s_add_i32 m0, s97, 0x16000
	s_add_u32 s98, s62, s8
	global_load_lds_dwordx4 v132, s[10:11]
	s_addc_u32 s99, s63, s9
	s_add_i32 s10, s97, 0x2000
	s_mov_b32 m0, s97
	s_add_u32 s8, s98, 0x40000
	global_load_lds_dwordx4 v138, s[98:99]
	s_mov_b32 m0, s10
	s_addc_u32 s9, s99, 0
	s_add_i32 s11, s97, 0x4000
	global_load_lds_dwordx4 v134, s[98:99]
	s_mov_b32 m0, s11
	s_add_i32 s12, s97, 0x6000
	global_load_lds_dwordx4 v138, s[8:9]
	s_mov_b32 m0, s12
	v_writelane_b32 v244, s95, 25
	global_load_lds_dwordx4 v134, s[8:9]
	v_writelane_b32 v244, s92, 26
	v_mov_b32_e32 v141, 0
	v_mov_b32_e32 v137, v141
	v_writelane_b32 v244, s93, 27
	v_writelane_b32 v244, s34, 28
	v_mov_b32_e32 v133, v141
	v_mov_b32_e32 v139, v141
	v_mov_b32_e32 v135, v141
	s_cmp_eq_u32 s6, 1
	v_writelane_b32 v244, s35, 29
	s_mov_b64 s[34:35], s[30:31]
	s_mov_b64 s[30:31], s[28:29]
	s_mov_b32 s13, 0
	v_lshl_add_u64 v[6:7], s[0:1], 0, v[136:137]
	v_lshl_add_u64 v[4:5], s[0:1], 0, v[132:133]
	v_lshl_add_u64 v[0:1], s[98:99], 0, v[138:139]
	s_cselect_b64 s[50:51], -1, 0
	s_cmp_lg_u32 s6, 1
	v_lshl_add_u64 v[2:3], s[98:99], 0, v[134:135]
	s_cbranch_scc1 .LBB0_209
	s_barrier

; #define PG8_STAGE(bufoff, gbase, voff) do { _Pragma("unroll") for (int _i = 0; _i < 2; ++_i) \
;         __builtin_amdgcn_global_load_lds((const unsigned*)((const char*)(gbase) + (voff)[_i]), (PG8_LAS unsigned*)(lds + (bufoff) + ldsw + _i * 8192), 16, 0, 0); } while (0)
; #define PG8_LDA(dst, b, h) do { _Pragma("unroll") for (int m = 0; m < 4; ++m) _Pragma("unroll") for (int k = 0; k < 2; ++k) dst[m][k] = *(const PG8_LAS bf16x8*)(lds + PG8_SA(b, h) + aoff + m * 2048 + k * 1024); } while (0)
; #define PG8_LDB(dst, b, h) do { _Pragma("unroll") for (int n = 0; n < 2; ++n) _Pragma("unroll") for (int k = 0; k < 2; ++k) dst[n][k] = *(const PG8_LAS bf16x8*)(lds + PG8_SB(b, h) + boff + n * 2048 + k * 1024); } while (0)
; #define PG8_WAIT_V(n) asm volatile("s_waitcnt vmcnt(" #n ")" ::: "memory")
; #define PG8_WAIT_L(n) asm volatile("s_waitcnt lgkmcnt(" #n ")" ::: "memory")
; template <class Epi, class Sched, bool ALIGN_EPI = false, bool SP2 = false, bool ABLK = false>
; __device__ __forceinline__ void gemm_phase(PG8_LAS unsigned char* lds, const Gemm g, const Sched& S, const Epi& E) {
;     ...
;         const bool has_next = S.next(ui + 1, nxt);
;         const char* nA = has_next ? (const char*)g.A + (size_t)nxt.pm * tstepA : cA; const char* nB = has_next ? (const char*)g.Bt + (size_t)nxt.pn * tstep : cB;
;         for (int t = 0; t < nt; t += 2) {
;             if constexpr (Epi::MID) { if (t == nt / 2) E.mid(acc, cur, wr, wc, fr, fq); }
;             const bool last = (t == nt - 2);
;             const char* a1 = cA + (size_t)(t + 1) * kstepA;
;             const char* a2 = last ? nA : cA + (size_t)(t + 2) * kstepA; const char* b2 = last ? nB : cB + (size_t)(t + 2) * kstep;
;             const char* a3 = a2 + kstepA; const char* b3 = b2 + kstep;
;             if (last && has_next) S.a_ready(nxt);
;             if constexpr (SP2) {
;             PG8_LDB(B0, 0, 0); PG8_LDB(B1, 0, 1); PG8_SCHED; PG8_LDA(At, 0, 0); PG8_STAGE(PG8_SA(1, 1), a1 + hstepA, voffA);
;             PG8_WAIT_V(8); PG8_WAIT_L(0); PG8_BAR; PG8_MMA(0, 0, At, B0); PG8_MMA(0, 1, At, B1); PG8_BAR; PG8_SCHED;
;             PG8_LDA(At, 0, 1); PG8_STAGE(PG8_SB(0, 0), b2, voffB); PG8_STAGE(PG8_SB(0, 1), b2 + hstep, voffB); PG8_STAGE(PG8_SA(0, 0), a2, voffA);
;             PG8_WAIT_V(8); PG8_WAIT_L(0); PG8_BAR; PG8_MMA(1, 0, At, B0); PG8_MMA(1, 1, At, B1); PG8_BAR; PG8_SCHED;
.LBB0_214:
	s_ashr_i32 s5, s4, 31
	s_lshl_b64 s[6:7], s[4:5], 19
	s_add_u32 s8, s62, s6
	s_addc_u32 s9, s63, s7
	s_and_b64 s[6:7], s[36:37], exec
	s_cselect_b32 s5, s9, s99
	s_cselect_b32 s21, s8, s98
	s_ashr_i32 s95, s94, 31
	s_lshl_b64 s[6:7], s[94:95], 19
	s_add_u32 s6, s74, s6
	s_addc_u32 s7, s75, s7
	s_and_b64 s[22:23], s[36:37], exec
	s_cselect_b32 s95, s7, s1
	s_cselect_b32 s22, s6, s0
	s_add_u32 vcc_lo, s98, 0x40080
	s_addc_u32 vcc_hi, s99, 0
	s_add_u32 s23, s0, 0x100
	s_addc_u32 s24, s1, 0
	s_mov_b32 s25, -2
	ds_read_b128 v[166:169], v163
	ds_read_b128 v[170:173], v163 offset:1024
	ds_read_b128 v[180:183], v163 offset:2048
	ds_read_b128 v[184:187], v163 offset:3072
	ds_read_b128 v[188:191], v164
	ds_read_b128 v[192:195], v164 offset:1024
	ds_read_b128 v[196:199], v164 offset:2048
	ds_read_b128 v[200:203], v164 offset:3072
	s_add_u32 s0, vcc_lo, 0xfffc0080
	s_addc_u32 s1, vcc_hi, -1
	s_cmp_eq_u32 s25, 12
	s_cselect_b32 s99, s5, s1
	s_cselect_b32 s98, s21, s0
	s_cselect_b32 s1, s95, s24
	s_cselect_b32 s0, s22, s23
	v_lshl_add_u64 v[176:177], vcc, 0, v[142:143]
	s_add_i32 m0, s97, 0xc000
	ds_read_b128 v[204:207], v165
	ds_read_b128 v[208:211], v165 offset:1024
	ds_read_b128 v[212:215], v165 offset:2048
	ds_read_b128 v[216:219], v165 offset:3072
	ds_read_b128 v[220:223], v165 offset:4096
	ds_read_b128 v[224:227], v165 offset:5120
	ds_read_b128 v[228:231], v165 offset:6144
	ds_read_b128 v[232:235], v165 offset:7168
	global_load_lds_dwordx4 v[176:177], off
	v_lshl_add_u64 v[176:177], vcc, 0, v[144:145]
	s_add_i32 m0, s97, 0xe000
	s_nop 0
	global_load_lds_dwordx4 v[176:177], off
	s_cmp_eq_u32 s101, 16
	s_cbranch_scc1 .Lp1_w24_0
	s_cmp_eq_u32 s101, 8
	s_cbranch_scc1 .Lp1_w16_0
	s_waitcnt vmcnt(8)
	s_branch .Lp1_wd_0
.Lp1_w24_0:
	s_waitcnt vmcnt(24)
	s_branch .Lp1_wd_0
.Lp1_w16_0:
	s_waitcnt vmcnt(16)
.Lp1_wd_0:
	s_waitcnt lgkmcnt(0)
	s_barrier
	s_setprio 1
	s_waitcnt lgkmcnt(0)
	v_mfma_f32_16x16x32_bf16 v[124:127], v[166:169], v[204:207], 0
	v_mfma_f32_16x16x32_bf16 v[120:123], v[180:183], v[204:207], 0
	v_mfma_f32_16x16x32_bf16 v[116:119], v[166:169], v[212:215], 0
	v_mfma_f32_16x16x32_bf16 v[108:111], v[180:183], v[212:215], 0
	v_mfma_f32_16x16x32_bf16 v[100:103], v[166:169], v[220:223], 0
	v_mfma_f32_16x16x32_bf16 v[92:95], v[180:183], v[220:223], 0
	v_mfma_f32_16x16x32_bf16 v[84:87], v[166:169], v[228:231], 0
	v_mfma_f32_16x16x32_bf16 v[76:79], v[180:183], v[228:231], 0
	v_mfma_f32_16x16x32_bf16 v[124:127], v[170:173], v[208:211], v[124:127]
	v_mfma_f32_16x16x32_bf16 v[120:123], v[184:187], v[208:211], v[120:123]
	v_mfma_f32_16x16x32_bf16 v[116:119], v[170:173], v[216:219], v[116:119]
	v_mfma_f32_16x16x32_bf16 v[108:111], v[184:187], v[216:219], v[108:111]
	v_mfma_f32_16x16x32_bf16 v[100:103], v[170:173], v[224:227], v[100:103]
	v_mfma_f32_16x16x32_bf16 v[92:95], v[184:187], v[224:227], v[92:95]
	v_mfma_f32_16x16x32_bf16 v[84:87], v[170:173], v[232:235], v[84:87]
	v_mfma_f32_16x16x32_bf16 v[76:79], v[184:187], v[232:235], v[76:79]
	s_setprio 0
	s_setprio 1
	v_mfma_f32_16x16x32_bf16 v[112:115], v[188:191], v[204:207], 0
	v_mfma_f32_16x16x32_bf16 v[104:107], v[196:199], v[204:207], 0
	v_mfma_f32_16x16x32_bf16 v[96:99], v[188:191], v[212:215], 0
	v_mfma_f32_16x16x32_bf16 v[88:91], v[196:199], v[212:215], 0
	v_mfma_f32_16x16x32_bf16 v[80:83], v[188:191], v[220:223], 0
	v_mfma_f32_16x16x32_bf16 v[72:75], v[196:199], v[220:223], 0
	v_mfma_f32_16x16x32_bf16 v[68:71], v[188:191], v[228:231], 0
	v_mfma_f32_16x16x32_bf16 v[64:67], v[196:199], v[228:231], 0
	v_mfma_f32_16x16x32_bf16 v[112:115], v[192:195], v[208:211], v[112:115]
	v_mfma_f32_16x16x32_bf16 v[104:107], v[200:203], v[208:211], v[104:107]
	v_mfma_f32_16x16x32_bf16 v[96:99], v[192:195], v[216:219], v[96:99]
	v_mfma_f32_16x16x32_bf16 v[88:91], v[200:203], v[216:219], v[88:91]
	v_mfma_f32_16x16x32_bf16 v[80:83], v[192:195], v[224:227], v[80:83]
	v_mfma_f32_16x16x32_bf16 v[72:75], v[200:203], v[224:227], v[72:75]
	v_mfma_f32_16x16x32_bf16 v[68:71], v[192:195], v[232:235], v[68:71]
	v_mfma_f32_16x16x32_bf16 v[64:67], v[200:203], v[232:235], v[64:67]
	s_setprio 0
	s_barrier
	s_add_i32 s26, s17, s46
	v_lshl_add_u64 v[176:177], s[0:1], 0, v[136:137]
	s_mov_b32 m0, s26
	ds_read_b128 v[204:207], v165 offset:16384
	ds_read_b128 v[208:211], v165 offset:17408
	ds_read_b128 v[212:215], v165 offset:18432
	ds_read_b128 v[216:219], v165 offset:19456
	ds_read_b128 v[220:223], v165 offset:20480
	ds_read_b128 v[224:227], v165 offset:21504
	ds_read_b128 v[228:231], v165 offset:22528
	ds_read_b128 v[232:235], v165 offset:23552
	global_load_lds_dwordx4 v[176:177], off
	s_add_i32 m0, s26, 0x2000
	s_add_u32 s26, s0, 0x40000
	v_lshl_add_u64 v[236:237], s[0:1], 0, v[132:133]
	s_addc_u32 s27, s1, 0
	s_add_i32 s28, s18, s46
	global_load_lds_dwordx4 v[236:237], off
	v_lshl_add_u64 v[238:239], s[26:27], 0, v[136:137]
	s_mov_b32 m0, s28
	v_lshl_add_u64 v[240:241], s[98:99], 0, v[134:135]
	global_load_lds_dwordx4 v[238:239], off
	v_lshl_add_u64 v[238:239], s[26:27], 0, v[132:133]
	s_add_i32 m0, s28, 0x2000
	s_nop 0
	global_load_lds_dwordx4 v[238:239], off
	v_lshl_add_u64 v[238:239], s[98:99], 0, v[138:139]
	s_mov_b32 m0, s97
	s_nop 0
	global_load_lds_dwordx4 v[238:239], off
	s_mov_b32 m0, s10
	s_nop 0
	global_load_lds_dwordx4 v[240:241], off
	s_cmp_eq_u32 s101, 16
	s_cbranch_scc1 .Lp1_w24_1
	s_cmp_eq_u32 s101, 8
	s_cbranch_scc1 .Lp1_w16_1
	s_waitcnt vmcnt(8)
	s_branch .Lp1_wd_1

; #define PG8_STAGE(bufoff, gbase, voff) do { _Pragma("unroll") for (int _i = 0; _i < 2; ++_i) \
;         __builtin_amdgcn_global_load_lds((const unsigned*)((const char*)(gbase) + (voff)[_i]), (PG8_LAS unsigned*)(lds + (bufoff) + ldsw + _i * 8192), 16, 0, 0); } while (0)
; #define PG8_LDA(dst, b, h) do { _Pragma("unroll") for (int m = 0; m < 4; ++m) _Pragma("unroll") for (int k = 0; k < 2; ++k) dst[m][k] = *(const PG8_LAS bf16x8*)(lds + PG8_SA(b, h) + aoff + m * 2048 + k * 1024); } while (0)
; #define PG8_LDB(dst, b, h) do { _Pragma("unroll") for (int n = 0; n < 2; ++n) _Pragma("unroll") for (int k = 0; k < 2; ++k) dst[n][k] = *(const PG8_LAS bf16x8*)(lds + PG8_SB(b, h) + boff + n * 2048 + k * 1024); } while (0)
; #define PG8_MMA(ai, bj, At, Bt) do { __builtin_amdgcn_s_setprio(1); _Pragma("unroll") for (int m = 0; m < 4; ++m) _Pragma("unroll") for (int n = 0; n < 2; ++n) _Pragma("unroll") for (int k = 0; k < 2; ++k) \
;         acc[ai][bj][m][n] = __builtin_amdgcn_mfma_f32_16x16x32_bf16(Bt[n][k], At[m][k], acc[ai][bj][m][n], 0, 0, 0); __builtin_amdgcn_s_setprio(0); } while (0)
; #define PG8_WAIT_V(n) asm volatile("s_waitcnt vmcnt(" #n ")" ::: "memory")
; #define PG8_WAIT_L(n) asm volatile("s_waitcnt lgkmcnt(" #n ")" ::: "memory")
; #define PG8_BAR __builtin_amdgcn_s_barrier()
; #define PG8_SCHED __builtin_amdgcn_sched_barrier(0)
; template <class Epi, class Sched, bool ALIGN_EPI = false, bool SP2 = false, bool ABLK = false>
; __device__ __forceinline__ void gemm_phase(PG8_LAS unsigned char* lds, const Gemm g, const Sched& S, const Epi& E) {
;     ...
;             PG8_WAIT_V(8); PG8_WAIT_L(0); PG8_BAR; PG8_MMA(1, 0, At, B0); PG8_MMA(1, 1, At, B1); PG8_BAR; PG8_SCHED;
;             PG8_LDB(B0, 1, 0); PG8_LDB(B1, 1, 1); PG8_SCHED; PG8_LDA(At, 1, 0); PG8_STAGE(PG8_SA(0, 1), a2 + hstepA, voffA);
;             PG8_WAIT_V(8); PG8_WAIT_L(0); PG8_BAR; PG8_MMA(0, 0, At, B0); PG8_MMA(0, 1, At, B1); PG8_BAR; PG8_SCHED;
.Lp1_wd_1:
	s_waitcnt lgkmcnt(0)
	s_barrier
	s_setprio 1
	s_waitcnt lgkmcnt(0)
	v_mfma_f32_16x16x32_bf16 v[60:63], v[166:169], v[204:207], 0
	v_mfma_f32_16x16x32_bf16 v[56:59], v[180:183], v[204:207], 0
	v_mfma_f32_16x16x32_bf16 v[52:55], v[166:169], v[212:215], 0
	v_mfma_f32_16x16x32_bf16 v[44:47], v[180:183], v[212:215], 0
	v_mfma_f32_16x16x32_bf16 v[36:39], v[166:169], v[220:223], 0
	v_mfma_f32_16x16x32_bf16 v[28:31], v[180:183], v[220:223], 0
	v_mfma_f32_16x16x32_bf16 v[20:23], v[166:169], v[228:231], 0
	v_mfma_f32_16x16x32_bf16 v[12:15], v[180:183], v[228:231], 0
	v_mfma_f32_16x16x32_bf16 v[60:63], v[170:173], v[208:211], v[60:63]
	v_mfma_f32_16x16x32_bf16 v[56:59], v[184:187], v[208:211], v[56:59]
	v_mfma_f32_16x16x32_bf16 v[52:55], v[170:173], v[216:219], v[52:55]
	v_mfma_f32_16x16x32_bf16 v[44:47], v[184:187], v[216:219], v[44:47]
	v_mfma_f32_16x16x32_bf16 v[36:39], v[170:173], v[224:227], v[36:39]
	v_mfma_f32_16x16x32_bf16 v[28:31], v[184:187], v[224:227], v[28:31]
	v_mfma_f32_16x16x32_bf16 v[20:23], v[170:173], v[232:235], v[20:23]
	v_mfma_f32_16x16x32_bf16 v[12:15], v[184:187], v[232:235], v[12:15]
	s_setprio 0
	s_setprio 1
	v_mfma_f32_16x16x32_bf16 v[48:51], v[188:191], v[204:207], 0
	v_mfma_f32_16x16x32_bf16 v[40:43], v[196:199], v[204:207], 0
	v_mfma_f32_16x16x32_bf16 v[32:35], v[188:191], v[212:215], 0
	v_mfma_f32_16x16x32_bf16 v[24:27], v[196:199], v[212:215], 0
	v_mfma_f32_16x16x32_bf16 v[16:19], v[188:191], v[220:223], 0
	v_mfma_f32_16x16x32_bf16 v[8:11], v[196:199], v[220:223], 0
	v_mfma_f32_16x16x32_bf16 v[4:7], v[188:191], v[228:231], 0
	v_mfma_f32_16x16x32_bf16 v[0:3], v[196:199], v[228:231], 0
	v_mfma_f32_16x16x32_bf16 v[48:51], v[192:195], v[208:211], v[48:51]
	v_mfma_f32_16x16x32_bf16 v[40:43], v[200:203], v[208:211], v[40:43]
	v_mfma_f32_16x16x32_bf16 v[32:35], v[192:195], v[216:219], v[32:35]
	v_mfma_f32_16x16x32_bf16 v[24:27], v[200:203], v[216:219], v[24:27]
	v_mfma_f32_16x16x32_bf16 v[16:19], v[192:195], v[224:227], v[16:19]
	v_mfma_f32_16x16x32_bf16 v[8:11], v[200:203], v[224:227], v[8:11]
	v_mfma_f32_16x16x32_bf16 v[4:7], v[192:195], v[232:235], v[4:7]
	v_mfma_f32_16x16x32_bf16 v[0:3], v[200:203], v[232:235], v[0:3]
	s_setprio 0
	s_barrier
	s_add_i32 s28, 0, 0x18000
	v_add_u32_e32 v140, s28, v161
	s_add_i32 s29, 0, 0x1c000
	ds_read_b128 v[166:169], v140
	ds_read_b128 v[170:173], v140 offset:1024
	ds_read_b128 v[180:183], v140 offset:2048
	ds_read_b128 v[184:187], v140 offset:3072
	v_add_u32_e32 v140, s29, v161
	ds_read_b128 v[188:191], v140
	ds_read_b128 v[192:195], v140 offset:1024
	ds_read_b128 v[196:199], v140 offset:2048
	ds_read_b128 v[200:203], v140 offset:3072
	s_add_u32 s26, s98, 0x40000
	s_addc_u32 s27, s99, 0
	s_mov_b32 m0, s11
	v_lshl_add_u64 v[242:243], s[26:27], 0, v[138:139]
	ds_read_b128 v[204:207], v165 offset:32768
	ds_read_b128 v[208:211], v165 offset:33792
	ds_read_b128 v[212:215], v165 offset:34816
	ds_read_b128 v[216:219], v165 offset:35840
	ds_read_b128 v[220:223], v165 offset:36864
	ds_read_b128 v[224:227], v165 offset:37888
	ds_read_b128 v[228:231], v165 offset:38912
	ds_read_b128 v[232:235], v165 offset:39936
	global_load_lds_dwordx4 v[242:243], off
	v_lshl_add_u64 v[242:243], s[26:27], 0, v[134:135]
	s_mov_b32 m0, s12
	s_nop 0
	global_load_lds_dwordx4 v[242:243], off
	s_waitcnt vmcnt(8)
	s_waitcnt lgkmcnt(0)
	s_barrier
	s_setprio 1
	s_waitcnt lgkmcnt(0)
	v_mfma_f32_16x16x32_bf16 v[124:127], v[166:169], v[204:207], v[124:127]
	v_mfma_f32_16x16x32_bf16 v[120:123], v[180:183], v[204:207], v[120:123]
	v_mfma_f32_16x16x32_bf16 v[116:119], v[166:169], v[212:215], v[116:119]
	v_mfma_f32_16x16x32_bf16 v[108:111], v[180:183], v[212:215], v[108:111]
	v_mfma_f32_16x16x32_bf16 v[100:103], v[166:169], v[220:223], v[100:103]
	v_mfma_f32_16x16x32_bf16 v[92:95], v[180:183], v[220:223], v[92:95]
	v_mfma_f32_16x16x32_bf16 v[84:87], v[166:169], v[228:231], v[84:87]
	v_mfma_f32_16x16x32_bf16 v[76:79], v[180:183], v[228:231], v[76:79]
	v_mfma_f32_16x16x32_bf16 v[124:127], v[170:173], v[208:211], v[124:127]
	v_mfma_f32_16x16x32_bf16 v[120:123], v[184:187], v[208:211], v[120:123]
	v_mfma_f32_16x16x32_bf16 v[116:119], v[170:173], v[216:219], v[116:119]
	v_mfma_f32_16x16x32_bf16 v[108:111], v[184:187], v[216:219], v[108:111]
	v_mfma_f32_16x16x32_bf16 v[100:103], v[170:173], v[224:227], v[100:103]
	v_mfma_f32_16x16x32_bf16 v[92:95], v[184:187], v[224:227], v[92:95]
	v_mfma_f32_16x16x32_bf16 v[84:87], v[170:173], v[232:235], v[84:87]
	v_mfma_f32_16x16x32_bf16 v[76:79], v[184:187], v[232:235], v[76:79]
	s_setprio 0
	s_setprio 1
	v_mfma_f32_16x16x32_bf16 v[112:115], v[188:191], v[204:207], v[112:115]
	v_mfma_f32_16x16x32_bf16 v[104:107], v[196:199], v[204:207], v[104:107]
	v_mfma_f32_16x16x32_bf16 v[96:99], v[188:191], v[212:215], v[96:99]
	v_mfma_f32_16x16x32_bf16 v[88:91], v[196:199], v[212:215], v[88:91]
	v_mfma_f32_16x16x32_bf16 v[80:83], v[188:191], v[220:223], v[80:83]
	v_mfma_f32_16x16x32_bf16 v[72:75], v[196:199], v[220:223], v[72:75]
	v_mfma_f32_16x16x32_bf16 v[68:71], v[188:191], v[228:231], v[68:71]
	v_mfma_f32_16x16x32_bf16 v[64:67], v[196:199], v[228:231], v[64:67]
	v_mfma_f32_16x16x32_bf16 v[112:115], v[192:195], v[208:211], v[112:115]
	v_mfma_f32_16x16x32_bf16 v[104:107], v[200:203], v[208:211], v[104:107]
	v_mfma_f32_16x16x32_bf16 v[96:99], v[192:195], v[216:219], v[96:99]
	v_mfma_f32_16x16x32_bf16 v[88:91], v[200:203], v[216:219], v[88:91]
	v_mfma_f32_16x16x32_bf16 v[80:83], v[192:195], v[224:227], v[80:83]
	v_mfma_f32_16x16x32_bf16 v[72:75], v[200:203], v[224:227], v[72:75]
	v_mfma_f32_16x16x32_bf16 v[68:71], v[192:195], v[232:235], v[68:71]
	v_mfma_f32_16x16x32_bf16 v[64:67], v[200:203], v[232:235], v[64:67]
	s_setprio 0
	s_barrier
; #define PG8_STAGE(bufoff, gbase, voff) do { _Pragma("unroll") for (int _i = 0; _i < 2; ++_i) \
;         __builtin_amdgcn_global_load_lds((const unsigned*)((const char*)(gbase) + (voff)[_i]), (PG8_LAS unsigned*)(lds + (bufoff) + ldsw + _i * 8192), 16, 0, 0); } while (0)
; #define PG8_LDA(dst, b, h) do { _Pragma("unroll") for (int m = 0; m < 4; ++m) _Pragma("unroll") for (int k = 0; k < 2; ++k) dst[m][k] = *(const PG8_LAS bf16x8*)(lds + PG8_SA(b, h) + aoff + m * 2048 + k * 1024); } while (0)
; #define PG8_MMA(ai, bj, At, Bt) do { __builtin_amdgcn_s_setprio(1); _Pragma("unroll") for (int m = 0; m < 4; ++m) _Pragma("unroll") for (int n = 0; n < 2; ++n) _Pragma("unroll") for (int k = 0; k < 2; ++k) \
;         acc[ai][bj][m][n] = __builtin_amdgcn_mfma_f32_16x16x32_bf16(Bt[n][k], At[m][k], acc[ai][bj][m][n], 0, 0, 0); __builtin_amdgcn_s_setprio(0); } while (0)
; #define PG8_WAIT_V(n) asm volatile("s_waitcnt vmcnt(" #n ")" ::: "memory")
; #define PG8_WAIT_L(n) asm volatile("s_waitcnt lgkmcnt(" #n ")" ::: "memory")
; #define PG8_BAR __builtin_amdgcn_s_barrier()
; #define PG8_SCHED __builtin_amdgcn_sched_barrier(0)
; template <class Epi, class Sched, bool ALIGN_EPI = false, bool SP2 = false, bool ABLK = false>
; __device__ __forceinline__ void gemm_phase(PG8_LAS unsigned char* lds, const Gemm g, const Sched& S, const Epi& E) {
;     ...
;         for (int t = 0; t < nt; t += 2) {
;     ...
;             PG8_LDA(At, 1, 1); PG8_STAGE(PG8_SB(1, 0), b3, voffB); PG8_STAGE(PG8_SB(1, 1), b3 + hstep, voffB); PG8_STAGE(PG8_SA(1, 0), a3, voffA);
;             PG8_WAIT_V(8); PG8_WAIT_L(0); PG8_BAR; PG8_MMA(1, 0, At, B0); PG8_MMA(1, 1, At, B1); PG8_BAR; PG8_SCHED;
	s_add_i32 s26, s28, s46
	v_lshl_add_u64 v[176:177], v[176:177], 0, s[52:53]
	s_mov_b32 m0, s26
	ds_read_b128 v[204:207], v165 offset:49152
	ds_read_b128 v[208:211], v165 offset:50176
	ds_read_b128 v[212:215], v165 offset:51200
	ds_read_b128 v[216:219], v165 offset:52224
	ds_read_b128 v[220:223], v165 offset:53248
	ds_read_b128 v[224:227], v165 offset:54272
	ds_read_b128 v[228:231], v165 offset:55296
	ds_read_b128 v[232:235], v165 offset:56320
	global_load_lds_dwordx4 v[176:177], off
	s_add_i32 m0, s26, 0x2000
	s_add_u32 s0, s0, 0x40080
	v_lshl_add_u64 v[176:177], v[236:237], 0, s[52:53]
	s_addc_u32 s1, s1, 0
	s_add_i32 s26, s29, s46
	global_load_lds_dwordx4 v[176:177], off
	v_lshl_add_u64 v[176:177], s[0:1], 0, v[136:137]
	s_mov_b32 m0, s26
	s_nop 0
	global_load_lds_dwordx4 v[176:177], off
	v_lshl_add_u64 v[176:177], s[0:1], 0, v[132:133]
	s_add_i32 m0, s26, 0x2000
	s_nop 0
	global_load_lds_dwordx4 v[176:177], off
	v_lshl_add_u64 v[176:177], v[238:239], 0, s[52:53]
	s_mov_b32 m0, s14
	s_nop 0
	global_load_lds_dwordx4 v[176:177], off
	v_lshl_add_u64 v[176:177], v[240:241], 0, s[52:53]
	s_mov_b32 m0, s15
	s_nop 0
	global_load_lds_dwordx4 v[176:177], off
	s_waitcnt vmcnt(8)
	s_waitcnt lgkmcnt(0)
	s_barrier
	s_setprio 1
	s_waitcnt lgkmcnt(0)
	v_mfma_f32_16x16x32_bf16 v[60:63], v[166:169], v[204:207], v[60:63]
	v_mfma_f32_16x16x32_bf16 v[56:59], v[180:183], v[204:207], v[56:59]
	v_mfma_f32_16x16x32_bf16 v[52:55], v[166:169], v[212:215], v[52:55]
	v_mfma_f32_16x16x32_bf16 v[44:47], v[180:183], v[212:215], v[44:47]
	v_mfma_f32_16x16x32_bf16 v[36:39], v[166:169], v[220:223], v[36:39]
	v_mfma_f32_16x16x32_bf16 v[28:31], v[180:183], v[220:223], v[28:31]
	v_mfma_f32_16x16x32_bf16 v[20:23], v[166:169], v[228:231], v[20:23]
	v_mfma_f32_16x16x32_bf16 v[12:15], v[180:183], v[228:231], v[12:15]
	v_mfma_f32_16x16x32_bf16 v[60:63], v[170:173], v[208:211], v[60:63]
	v_mfma_f32_16x16x32_bf16 v[56:59], v[184:187], v[208:211], v[56:59]
	v_mfma_f32_16x16x32_bf16 v[52:55], v[170:173], v[216:219], v[52:55]
	v_mfma_f32_16x16x32_bf16 v[44:47], v[184:187], v[216:219], v[44:47]
	v_mfma_f32_16x16x32_bf16 v[36:39], v[170:173], v[224:227], v[36:39]
	v_mfma_f32_16x16x32_bf16 v[28:31], v[184:187], v[224:227], v[28:31]
	v_mfma_f32_16x16x32_bf16 v[20:23], v[170:173], v[232:235], v[20:23]
	v_mfma_f32_16x16x32_bf16 v[12:15], v[184:187], v[232:235], v[12:15]
	s_setprio 0
	s_setprio 1
	v_mfma_f32_16x16x32_bf16 v[48:51], v[188:191], v[204:207], v[48:51]
	v_mfma_f32_16x16x32_bf16 v[40:43], v[196:199], v[204:207], v[40:43]
	v_mfma_f32_16x16x32_bf16 v[32:35], v[188:191], v[212:215], v[32:35]
	v_mfma_f32_16x16x32_bf16 v[24:27], v[196:199], v[212:215], v[24:27]
	v_mfma_f32_16x16x32_bf16 v[16:19], v[188:191], v[220:223], v[16:19]
	v_mfma_f32_16x16x32_bf16 v[8:11], v[196:199], v[220:223], v[8:11]
	v_mfma_f32_16x16x32_bf16 v[4:7], v[188:191], v[228:231], v[4:7]
	v_mfma_f32_16x16x32_bf16 v[0:3], v[196:199], v[228:231], v[0:3]
	v_mfma_f32_16x16x32_bf16 v[48:51], v[192:195], v[208:211], v[48:51]
	v_mfma_f32_16x16x32_bf16 v[40:43], v[200:203], v[208:211], v[40:43]
	v_mfma_f32_16x16x32_bf16 v[32:35], v[192:195], v[216:219], v[32:35]
	v_mfma_f32_16x16x32_bf16 v[24:27], v[200:203], v[216:219], v[24:27]
	v_mfma_f32_16x16x32_bf16 v[16:19], v[192:195], v[224:227], v[16:19]
	v_mfma_f32_16x16x32_bf16 v[8:11], v[200:203], v[224:227], v[8:11]
	v_mfma_f32_16x16x32_bf16 v[4:7], v[192:195], v[232:235], v[4:7]
	v_mfma_f32_16x16x32_bf16 v[0:3], v[200:203], v[232:235], v[0:3]
	s_setprio 0
	s_barrier
	s_add_i32 s25, s25, 2
	s_add_u32 vcc_lo, vcc_lo, 0x100
	s_addc_u32 vcc_hi, vcc_hi, 0
	s_add_u32 s23, s23, 0x100
	s_addc_u32 s24, s24, 0
	s_cmp_gt_u32 s25, 13
	s_cbranch_scc0 .LBB0_215
	s_branch .Lp1_kdone

; __device__ __forceinline__ unsigned cvt_pk_bf16(float lo, float hi) { unsigned r; asm volatile("v_cvt_pk_bf16_f32 %0, %1, %2" : "=v"(r) : "v"(lo), "v"(hi)); return r; }
;     __device__ __forceinline__ void operator()(const f32x4 (&acc)[2][2][4][2], const Unit& u, int wr, int wc, int fr, int fq) const {
;     ...
;             const int col0 = 1280 + (u.pn - 5) * HALF + wc * 32 + 8 * fq;
; #pragma unroll
;             for (int ai = 0; ai < 2; ++ai)
; #pragma unroll
;                 for (int m = 0; m < 4; ++m) { const f32x4 v0 = acc[ai][0][m][0] * acc[ai][1][m][0], v1 = acc[ai][0][m][1] * acc[ai][1][m][1];
;                     u32x4 w; w.x = cvt_pk_bf16(v0[0], v0[1]); w.y = cvt_pk_bf16(v0[2], v0[3]); w.z = cvt_pk_bf16(v1[0], v1[1]); w.w = cvt_pk_bf16(v1[2], v1[3]);
;                     *(u32x4*)(O + (size_t)(row0 + ai * HALF + m * 16) * ldc + col0) = w; }
.LBB0_221:
	s_mov_b32 s101, 8
	v_pk_mul_f32 v[176:177], v[126:127], v[114:115]
	v_pk_mul_f32 v[180:181], v[124:125], v[112:113]
	v_pk_mul_f32 v[184:185], v[122:123], v[106:107]
	v_pk_mul_f32 v[182:183], v[120:121], v[104:105]
	v_cvt_pk_bf16_f32 v180, v180, v181
	v_cvt_pk_bf16_f32 v181, v176, v177
	v_mov_b64_e32 v[176:177], s[66:67]
	v_lshlrev_b32_e32 v140, 1, v162
	v_cvt_pk_bf16_f32 v182, v182, v183
	v_cvt_pk_bf16_f32 v183, v184, v185
	v_mad_i64_i32 v[184:185], s[0:1], v173, s19, v[176:177]
	v_lshl_or_b32 v140, s20, 8, v140
	v_lshl_add_u64 v[184:185], v[184:185], 0, v[140:141]
	global_store_dwordx4 v[184:185], v[180:183], off offset:1280
	v_pk_mul_f32 v[184:185], v[110:111], v[90:91]
	v_pk_mul_f32 v[186:187], v[108:109], v[88:89]
	v_pk_mul_f32 v[182:183], v[118:119], v[98:99]
	v_pk_mul_f32 v[180:181], v[116:117], v[96:97]
	s_nop 0
	v_cvt_pk_bf16_f32 v180, v180, v181
	v_cvt_pk_bf16_f32 v181, v182, v183
	v_cvt_pk_bf16_f32 v182, v186, v187
	v_cvt_pk_bf16_f32 v183, v184, v185
	v_mad_i64_i32 v[184:185], s[0:1], v172, s19, v[176:177]
	v_lshl_add_u64 v[184:185], v[184:185], 0, v[140:141]
	global_store_dwordx4 v[184:185], v[180:183], off offset:1280
	v_pk_mul_f32 v[184:185], v[94:95], v[74:75]
	v_pk_mul_f32 v[186:187], v[92:93], v[72:73]
	v_pk_mul_f32 v[182:183], v[102:103], v[82:83]
	v_pk_mul_f32 v[180:181], v[100:101], v[80:81]
	s_nop 0
	v_cvt_pk_bf16_f32 v180, v180, v181
	v_cvt_pk_bf16_f32 v181, v182, v183
	v_cvt_pk_bf16_f32 v182, v186, v187
	v_cvt_pk_bf16_f32 v183, v184, v185
	v_mad_i64_i32 v[184:185], s[0:1], v171, s19, v[176:177]
	v_lshl_add_u64 v[184:185], v[184:185], 0, v[140:141]
	global_store_dwordx4 v[184:185], v[180:183], off offset:1280
	v_pk_mul_f32 v[184:185], v[78:79], v[66:67]
	v_pk_mul_f32 v[186:187], v[76:77], v[64:65]
	v_pk_mul_f32 v[182:183], v[86:87], v[70:71]
	v_pk_mul_f32 v[180:181], v[84:85], v[68:69]
	s_nop 0
	v_cvt_pk_bf16_f32 v180, v180, v181
	v_cvt_pk_bf16_f32 v181, v182, v183
	v_cvt_pk_bf16_f32 v182, v186, v187
	v_cvt_pk_bf16_f32 v183, v184, v185
	v_mad_i64_i32 v[184:185], s[0:1], v170, s19, v[176:177]
	v_lshl_add_u64 v[184:185], v[184:185], 0, v[140:141]
	global_store_dwordx4 v[184:185], v[180:183], off offset:1280
	v_pk_mul_f32 v[184:185], v[58:59], v[42:43]
	v_pk_mul_f32 v[186:187], v[56:57], v[40:41]
	v_pk_mul_f32 v[182:183], v[62:63], v[50:51]
	v_pk_mul_f32 v[180:181], v[60:61], v[48:49]
	s_nop 0
	v_cvt_pk_bf16_f32 v180, v180, v181
	v_cvt_pk_bf16_f32 v181, v182, v183
	v_cvt_pk_bf16_f32 v182, v186, v187
	v_cvt_pk_bf16_f32 v183, v184, v185
	v_mad_i64_i32 v[184:185], s[0:1], v169, s19, v[176:177]
	v_lshl_add_u64 v[184:185], v[184:185], 0, v[140:141]
	global_store_dwordx4 v[184:185], v[180:183], off offset:1280
	v_pk_mul_f32 v[184:185], v[46:47], v[26:27]
	v_pk_mul_f32 v[186:187], v[44:45], v[24:25]
	v_pk_mul_f32 v[182:183], v[54:55], v[34:35]
	v_pk_mul_f32 v[180:181], v[52:53], v[32:33]
	s_nop 0
	v_cvt_pk_bf16_f32 v180, v180, v181
	v_cvt_pk_bf16_f32 v181, v182, v183
	v_cvt_pk_bf16_f32 v182, v186, v187
	v_cvt_pk_bf16_f32 v183, v184, v185
	v_mad_i64_i32 v[184:185], s[0:1], v168, s19, v[176:177]
	v_lshl_add_u64 v[184:185], v[184:185], 0, v[140:141]
	global_store_dwordx4 v[184:185], v[180:183], off offset:1280
	v_pk_mul_f32 v[184:185], v[30:31], v[10:11]
	v_pk_mul_f32 v[186:187], v[28:29], v[8:9]
	v_pk_mul_f32 v[182:183], v[38:39], v[18:19]
	v_pk_mul_f32 v[180:181], v[36:37], v[16:17]
	s_nop 0
	v_cvt_pk_bf16_f32 v180, v180, v181
	v_cvt_pk_bf16_f32 v181, v182, v183
	v_cvt_pk_bf16_f32 v182, v186, v187
	v_cvt_pk_bf16_f32 v183, v184, v185
	v_mad_i64_i32 v[184:185], s[0:1], v167, s19, v[176:177]
	v_lshl_add_u64 v[184:185], v[184:185], 0, v[140:141]
	v_mad_i64_i32 v[176:177], s[0:1], v166, s19, v[176:177]
	global_store_dwordx4 v[184:185], v[180:183], off offset:1280
	v_lshl_add_u64 v[176:177], v[176:177], 0, v[140:141]
	v_pk_mul_f32 v[184:185], v[14:15], v[2:3]
	v_pk_mul_f32 v[182:183], v[22:23], v[6:7]
	v_pk_mul_f32 v[180:181], v[20:21], v[4:5]
	v_pk_mul_f32 v[186:187], v[12:13], v[0:1]
	v_cvt_pk_bf16_f32 v180, v180, v181
	v_cvt_pk_bf16_f32 v181, v182, v183
	s_nop 0
	v_cvt_pk_bf16_f32 v182, v186, v187
	v_cvt_pk_bf16_f32 v183, v184, v185
	global_store_dwordx4 v[176:177], v[180:183], off offset:1280
	s_cbranch_execnz .LBB0_220
; __device__ __forceinline__ unsigned cvt_pk_bf16(float lo, float hi) { unsigned r; asm volatile("v_cvt_pk_bf16_f32 %0, %1, %2" : "=v"(r) : "v"(lo), "v"(hi)); return r; }
;     __device__ __forceinline__ void operator()(const f32x4 (&acc)[2][2][4][2], const Unit& u, int wr, int wc, int fr, int fq) const {
;     ...
;             const int col0 = u.pn * BM + wc * 32 + 8 * fq;
; #pragma unroll
;             for (int ai = 0; ai < 2; ++ai)
; #pragma unroll
;                 for (int m = 0; m < 4; ++m) { bf16_t* rowp = O + (size_t)(row0 + ai * HALF + m * 16) * ldc + col0;
; #pragma unroll
;                     for (int bj = 0; bj < 2; ++bj) { const f32x4 v0 = acc[ai][bj][m][0], v1 = acc[ai][bj][m][1];
;                         u32x4 w; w.x = cvt_pk_bf16(v0[0], v0[1]); w.y = cvt_pk_bf16(v0[2], v0[3]); w.z = cvt_pk_bf16(v1[0], v1[1]); w.w = cvt_pk_bf16(v1[2], v1[3]);
;                         *(u32x4*)(rowp + bj * HALF) = w; } }
.LBB0_222:
	s_mov_b32 s101, 16
	v_lshl_or_b32 v176, s20, 8, v162
	v_ashrrev_i32_e32 v177, 31, v176
	v_mov_b64_e32 v[180:181], s[66:67]
	v_mad_i64_i32 v[182:183], s[0:1], v173, s19, v[180:181]
	v_lshlrev_b64 v[176:177], 1, v[176:177]
	v_lshl_add_u64 v[182:183], v[182:183], 0, v[176:177]
	v_cvt_pk_bf16_f32 v124, v124, v125
	v_cvt_pk_bf16_f32 v125, v126, v127
	v_cvt_pk_bf16_f32 v126, v120, v121
	v_cvt_pk_bf16_f32 v127, v122, v123
	global_store_dwordx4 v[182:183], v[124:127], off
	v_cvt_pk_bf16_f32 v112, v112, v113
	v_cvt_pk_bf16_f32 v113, v114, v115
	v_cvt_pk_bf16_f32 v114, v104, v105
	v_mad_i64_i32 v[104:105], s[0:1], v172, s19, v[180:181]
	v_cvt_pk_bf16_f32 v115, v106, v107
	global_store_dwordx4 v[182:183], v[112:115], off offset:256
	s_nop 1
	v_lshl_add_u64 v[112:113], v[104:105], 0, v[176:177]
	v_cvt_pk_bf16_f32 v104, v116, v117
	v_cvt_pk_bf16_f32 v105, v118, v119
	v_cvt_pk_bf16_f32 v106, v108, v109
	v_cvt_pk_bf16_f32 v107, v110, v111
	global_store_dwordx4 v[112:113], v[104:107], off
	v_cvt_pk_bf16_f32 v96, v96, v97
	v_cvt_pk_bf16_f32 v97, v98, v99
	v_cvt_pk_bf16_f32 v98, v88, v89
	v_mad_i64_i32 v[88:89], s[0:1], v171, s19, v[180:181]
	v_cvt_pk_bf16_f32 v99, v90, v91
	global_store_dwordx4 v[112:113], v[96:99], off offset:256
	s_nop 1
	v_lshl_add_u64 v[96:97], v[88:89], 0, v[176:177]
	v_cvt_pk_bf16_f32 v88, v100, v101
	v_cvt_pk_bf16_f32 v89, v102, v103
	v_cvt_pk_bf16_f32 v90, v92, v93
	v_cvt_pk_bf16_f32 v91, v94, v95
	global_store_dwordx4 v[96:97], v[88:91], off
	v_cvt_pk_bf16_f32 v80, v80, v81
	v_cvt_pk_bf16_f32 v81, v82, v83
	v_cvt_pk_bf16_f32 v82, v72, v73
	v_mad_i64_i32 v[72:73], s[0:1], v170, s19, v[180:181]
	v_cvt_pk_bf16_f32 v83, v74, v75
	global_store_dwordx4 v[96:97], v[80:83], off offset:256
	s_nop 1
	v_lshl_add_u64 v[80:81], v[72:73], 0, v[176:177]
	v_cvt_pk_bf16_f32 v72, v84, v85
	v_cvt_pk_bf16_f32 v73, v86, v87
	v_cvt_pk_bf16_f32 v74, v76, v77
	v_cvt_pk_bf16_f32 v75, v78, v79
	global_store_dwordx4 v[80:81], v[72:75], off
	v_cvt_pk_bf16_f32 v68, v68, v69
	v_cvt_pk_bf16_f32 v69, v70, v71
	v_cvt_pk_bf16_f32 v70, v64, v65
	v_mad_i64_i32 v[64:65], s[0:1], v169, s19, v[180:181]
	v_lshl_add_u64 v[64:65], v[64:65], 0, v[176:177]
	v_cvt_pk_bf16_f32 v71, v66, v67
	global_store_dwordx4 v[80:81], v[68:71], off offset:256
	v_cvt_pk_bf16_f32 v60, v60, v61
	v_cvt_pk_bf16_f32 v61, v62, v63
	v_cvt_pk_bf16_f32 v62, v56, v57
	v_cvt_pk_bf16_f32 v63, v58, v59
	global_store_dwordx4 v[64:65], v[60:63], off
	v_cvt_pk_bf16_f32 v48, v48, v49
	v_cvt_pk_bf16_f32 v49, v50, v51
	v_cvt_pk_bf16_f32 v50, v40, v41
	v_mad_i64_i32 v[40:41], s[0:1], v168, s19, v[180:181]
	v_cvt_pk_bf16_f32 v51, v42, v43
	global_store_dwordx4 v[64:65], v[48:51], off offset:256
	s_nop 1
	v_lshl_add_u64 v[48:49], v[40:41], 0, v[176:177]
	v_cvt_pk_bf16_f32 v40, v52, v53
	v_cvt_pk_bf16_f32 v41, v54, v55
	v_cvt_pk_bf16_f32 v42, v44, v45
	v_cvt_pk_bf16_f32 v43, v46, v47
	global_store_dwordx4 v[48:49], v[40:43], off
	v_cvt_pk_bf16_f32 v32, v32, v33
	v_cvt_pk_bf16_f32 v33, v34, v35
	v_cvt_pk_bf16_f32 v34, v24, v25
	v_mad_i64_i32 v[24:25], s[0:1], v167, s19, v[180:181]
	v_cvt_pk_bf16_f32 v35, v26, v27
	global_store_dwordx4 v[48:49], v[32:35], off offset:256
	s_nop 1
	v_lshl_add_u64 v[32:33], v[24:25], 0, v[176:177]
	v_cvt_pk_bf16_f32 v24, v36, v37
	v_cvt_pk_bf16_f32 v25, v38, v39
	v_cvt_pk_bf16_f32 v26, v28, v29
	v_cvt_pk_bf16_f32 v27, v30, v31
	global_store_dwordx4 v[32:33], v[24:27], off
	v_cvt_pk_bf16_f32 v16, v16, v17
	v_cvt_pk_bf16_f32 v17, v18, v19
	v_cvt_pk_bf16_f32 v18, v8, v9
	v_mad_i64_i32 v[8:9], s[0:1], v166, s19, v[180:181]
	v_cvt_pk_bf16_f32 v19, v10, v11
	global_store_dwordx4 v[32:33], v[16:19], off offset:256
	s_nop 1
	v_lshl_add_u64 v[16:17], v[8:9], 0, v[176:177]
	v_cvt_pk_bf16_f32 v8, v20, v21
	v_cvt_pk_bf16_f32 v9, v22, v23
	v_cvt_pk_bf16_f32 v10, v12, v13
	v_cvt_pk_bf16_f32 v11, v14, v15
	global_store_dwordx4 v[16:17], v[8:11], off
	v_cvt_pk_bf16_f32 v4, v4, v5
	v_cvt_pk_bf16_f32 v5, v6, v7
	v_cvt_pk_bf16_f32 v6, v0, v1
	v_cvt_pk_bf16_f32 v7, v2, v3
	global_store_dwordx4 v[16:17], v[4:7], off offset:256
	s_andn2_b64 vcc, exec, s[36:37]
	s_mov_b64 s[0:1], -1
	s_cbranch_vccnz .LBB0_211

; #define PG8_STAGE(bufoff, gbase, voff) do { _Pragma("unroll") for (int _i = 0; _i < 2; ++_i) \
;         __builtin_amdgcn_global_load_lds((const unsigned*)((const char*)(gbase) + (voff)[_i]), (PG8_LAS unsigned*)(lds + (bufoff) + ldsw + _i * 8192), 16, 0, 0); } while (0)
; #define PG8_LDA(dst, b, h) do { _Pragma("unroll") for (int m = 0; m < 4; ++m) _Pragma("unroll") for (int k = 0; k < 2; ++k) dst[m][k] = *(const PG8_LAS bf16x8*)(lds + PG8_SA(b, h) + aoff + m * 2048 + k * 1024); } while (0)
; #define PG8_LDB(dst, b, h) do { _Pragma("unroll") for (int n = 0; n < 2; ++n) _Pragma("unroll") for (int k = 0; k < 2; ++k) dst[n][k] = *(const PG8_LAS bf16x8*)(lds + PG8_SB(b, h) + boff + n * 2048 + k * 1024); } while (0)
; #define PG8_WAIT_V(n) asm volatile("s_waitcnt vmcnt(" #n ")" ::: "memory")
; #define PG8_WAIT_L(n) asm volatile("s_waitcnt lgkmcnt(" #n ")" ::: "memory")
; template <class Epi, class Sched, bool ALIGN_EPI = false, bool SP2 = false, bool ABLK = false>
; __device__ __forceinline__ void gemm_phase(PG8_LAS unsigned char* lds, const Gemm g, const Sched& S, const Epi& E) {
;     ...
;         const bool has_next = S.next(ui + 1, nxt);
;         const char* nA = has_next ? (const char*)g.A + (size_t)nxt.pm * tstepA : cA; const char* nB = has_next ? (const char*)g.Bt + (size_t)nxt.pn * tstep : cB;
;         for (int t = 0; t < nt; t += 2) {
;             if constexpr (Epi::MID) { if (t == nt / 2) E.mid(acc, cur, wr, wc, fr, fq); }
;             const bool last = (t == nt - 2);
;             const char* a1 = cA + (size_t)(t + 1) * kstepA;
;             const char* a2 = last ? nA : cA + (size_t)(t + 2) * kstepA; const char* b2 = last ? nB : cB + (size_t)(t + 2) * kstep;
;             const char* a3 = a2 + kstepA; const char* b3 = b2 + kstep;
;             if (last && has_next) S.a_ready(nxt);
;             if constexpr (SP2) {
;             PG8_LDB(B0, 0, 0); PG8_LDB(B1, 0, 1); PG8_SCHED; PG8_LDA(At, 0, 0); PG8_STAGE(PG8_SA(1, 1), a1 + hstepA, voffA);
;             PG8_WAIT_V(8); PG8_WAIT_L(0); PG8_BAR; PG8_MMA(0, 0, At, B0); PG8_MMA(0, 1, At, B1); PG8_BAR; PG8_SCHED;
;             PG8_LDA(At, 0, 1); PG8_STAGE(PG8_SB(0, 0), b2, voffB); PG8_STAGE(PG8_SB(0, 1), b2 + hstep, voffB); PG8_STAGE(PG8_SA(0, 0), a2, voffA);
;             PG8_WAIT_V(8); PG8_WAIT_L(0); PG8_BAR; PG8_MMA(1, 0, At, B0); PG8_MMA(1, 1, At, B1); PG8_BAR; PG8_SCHED;
.LBB0_533:
	s_ashr_i32 s21, s20, 31
	s_lshl_b64 s[8:9], s[20:21], 19
	s_add_u32 s24, s10, s8
	s_addc_u32 s25, s11, s9
	s_and_b64 s[8:9], s[26:27], exec
	s_cselect_b32 s7, s25, s37
	s_cselect_b32 s21, s24, s36
	s_ashr_i32 s23, s22, 31
	s_lshl_b64 s[8:9], s[22:23], 19
	s_add_u32 s28, s52, s8
	s_addc_u32 s29, s53, s9
	s_and_b64 s[8:9], s[26:27], exec
	s_cselect_b32 s23, s29, s35
	s_cselect_b32 s31, s28, s34
	s_add_u32 s61, s34, 0x100
	s_addc_u32 s62, s35, 0
	s_add_u32 s8, s36, 0xc000
	s_addc_u32 s9, s37, 0
	s_mov_b32 s63, -2
	ds_read_b128 v[128:131], v143
	ds_read_b128 v[176:179], v143 offset:1024
	ds_read_b128 v[180:183], v143 offset:2048
	ds_read_b128 v[184:187], v143 offset:3072
	ds_read_b128 v[188:191], v167
	ds_read_b128 v[192:195], v167 offset:1024
	ds_read_b128 v[196:199], v167 offset:2048
	ds_read_b128 v[200:203], v167 offset:3072
	s_add_u32 s2, s8, 0x4000
	s_addc_u32 s34, s9, 0
	s_cmp_eq_u32 s63, 12
	s_cselect_b32 s38, s21, s2
	s_cselect_b32 s39, s7, s34
	s_cselect_b32 s36, s31, s61
	s_cselect_b32 s37, s23, s62
	s_add_u32 s34, s38, 0x8000
	s_addc_u32 s35, s39, 0
	s_mov_b32 m0, s58
	v_lshl_add_u64 v[172:173], s[8:9], 0, v[162:163]
	ds_read_b128 v[204:207], v168
	ds_read_b128 v[208:211], v168 offset:1024
	ds_read_b128 v[212:215], v168 offset:2048
	ds_read_b128 v[216:219], v168 offset:3072
	ds_read_b128 v[220:223], v168 offset:4096
	ds_read_b128 v[224:227], v168 offset:5120
	ds_read_b128 v[228:231], v168 offset:6144
	ds_read_b128 v[232:235], v168 offset:7168
	global_load_lds_dwordx4 v[172:173], off
	v_lshl_add_u64 v[172:173], s[8:9], 0, v[164:165]
	s_mov_b32 m0, s59
	s_nop 0
	global_load_lds_dwordx4 v[172:173], off
	s_cmp_eq_u32 s100, -1
	s_cbranch_scc1 .Lp4_w8_0
	s_waitcnt vmcnt(24)
	s_branch .Lp4_wd_0
.Lp4_w8_0:
	s_waitcnt vmcnt(8)
.Lp4_wd_0:
	s_waitcnt lgkmcnt(0)
	s_barrier
	s_setprio 1
	s_waitcnt lgkmcnt(0)
	v_mfma_f32_16x16x32_bf16 v[124:127], v[128:131], v[204:207], 0
	v_mfma_f32_16x16x32_bf16 v[120:123], v[180:183], v[204:207], 0
	v_mfma_f32_16x16x32_bf16 v[108:111], v[128:131], v[212:215], 0
	v_mfma_f32_16x16x32_bf16 v[104:107], v[180:183], v[212:215], 0
	v_mfma_f32_16x16x32_bf16 v[92:95], v[128:131], v[220:223], 0
	v_mfma_f32_16x16x32_bf16 v[88:91], v[180:183], v[220:223], 0
	v_mfma_f32_16x16x32_bf16 v[76:79], v[128:131], v[228:231], 0
	v_mfma_f32_16x16x32_bf16 v[72:75], v[180:183], v[228:231], 0
	v_mfma_f32_16x16x32_bf16 v[124:127], v[176:179], v[208:211], v[124:127]
	v_mfma_f32_16x16x32_bf16 v[120:123], v[184:187], v[208:211], v[120:123]
	v_mfma_f32_16x16x32_bf16 v[108:111], v[176:179], v[216:219], v[108:111]
	v_mfma_f32_16x16x32_bf16 v[104:107], v[184:187], v[216:219], v[104:107]
	v_mfma_f32_16x16x32_bf16 v[92:95], v[176:179], v[224:227], v[92:95]
	v_mfma_f32_16x16x32_bf16 v[88:91], v[184:187], v[224:227], v[88:91]
	v_mfma_f32_16x16x32_bf16 v[76:79], v[176:179], v[232:235], v[76:79]
	v_mfma_f32_16x16x32_bf16 v[72:75], v[184:187], v[232:235], v[72:75]
	s_setprio 0
	s_setprio 1
	v_mfma_f32_16x16x32_bf16 v[116:119], v[188:191], v[204:207], 0
	v_mfma_f32_16x16x32_bf16 v[112:115], v[196:199], v[204:207], 0
	v_mfma_f32_16x16x32_bf16 v[100:103], v[188:191], v[212:215], 0
	v_mfma_f32_16x16x32_bf16 v[96:99], v[196:199], v[212:215], 0
	v_mfma_f32_16x16x32_bf16 v[84:87], v[188:191], v[220:223], 0
	v_mfma_f32_16x16x32_bf16 v[80:83], v[196:199], v[220:223], 0
	v_mfma_f32_16x16x32_bf16 v[68:71], v[188:191], v[228:231], 0
	v_mfma_f32_16x16x32_bf16 v[64:67], v[196:199], v[228:231], 0
	v_mfma_f32_16x16x32_bf16 v[116:119], v[192:195], v[208:211], v[116:119]
	v_mfma_f32_16x16x32_bf16 v[112:115], v[200:203], v[208:211], v[112:115]
	v_mfma_f32_16x16x32_bf16 v[100:103], v[192:195], v[216:219], v[100:103]
	v_mfma_f32_16x16x32_bf16 v[96:99], v[200:203], v[216:219], v[96:99]
	v_mfma_f32_16x16x32_bf16 v[84:87], v[192:195], v[224:227], v[84:87]
	v_mfma_f32_16x16x32_bf16 v[80:83], v[200:203], v[224:227], v[80:83]
	v_mfma_f32_16x16x32_bf16 v[68:71], v[192:195], v[232:235], v[68:71]
	v_mfma_f32_16x16x32_bf16 v[64:67], v[200:203], v[232:235], v[64:67]
	s_setprio 0
	s_barrier
	s_mov_b32 m0, s60
	v_lshl_add_u64 v[172:173], s[36:37], 0, v[136:137]
	ds_read_b128 v[204:207], v168 offset:16384
	ds_read_b128 v[208:211], v168 offset:17408
	ds_read_b128 v[212:215], v168 offset:18432
	ds_read_b128 v[216:219], v168 offset:19456
	ds_read_b128 v[220:223], v168 offset:20480
	ds_read_b128 v[224:227], v168 offset:21504
	ds_read_b128 v[228:231], v168 offset:22528
	ds_read_b128 v[232:235], v168 offset:23552
	global_load_lds_dwordx4 v[172:173], off
	s_add_i32 m0, s60, 0x2000
	s_add_u32 s70, s36, 0x40000
	v_lshl_add_u64 v[236:237], s[36:37], 0, v[132:133]
	s_addc_u32 s71, s37, 0
	s_add_i32 s2, s57, s3
	global_load_lds_dwordx4 v[236:237], off
	v_lshl_add_u64 v[238:239], s[70:71], 0, v[136:137]
	s_mov_b32 m0, s2
	s_nop 0
	global_load_lds_dwordx4 v[238:239], off
	v_lshl_add_u64 v[238:239], s[70:71], 0, v[132:133]
	s_add_i32 m0, s2, 0x2000
	s_nop 0
	global_load_lds_dwordx4 v[238:239], off
	v_lshl_add_u64 v[238:239], s[38:39], 0, v[138:139]
	s_mov_b32 m0, s40
	s_nop 0
	global_load_lds_dwordx4 v[238:239], off
	v_lshl_add_u64 v[238:239], s[38:39], 0, v[134:135]
	s_mov_b32 m0, s41
	s_nop 0
	global_load_lds_dwordx4 v[238:239], off
	s_cmp_eq_u32 s100, -1
	s_cbranch_scc1 .Lp4_w8_1
	s_waitcnt vmcnt(24)
	s_branch .Lp4_wd_1

; #define PG8_STAGE(bufoff, gbase, voff) do { _Pragma("unroll") for (int _i = 0; _i < 2; ++_i) \
;         __builtin_amdgcn_global_load_lds((const unsigned*)((const char*)(gbase) + (voff)[_i]), (PG8_LAS unsigned*)(lds + (bufoff) + ldsw + _i * 8192), 16, 0, 0); } while (0)
; #define PG8_LDA(dst, b, h) do { _Pragma("unroll") for (int m = 0; m < 4; ++m) _Pragma("unroll") for (int k = 0; k < 2; ++k) dst[m][k] = *(const PG8_LAS bf16x8*)(lds + PG8_SA(b, h) + aoff + m * 2048 + k * 1024); } while (0)
; #define PG8_LDB(dst, b, h) do { _Pragma("unroll") for (int n = 0; n < 2; ++n) _Pragma("unroll") for (int k = 0; k < 2; ++k) dst[n][k] = *(const PG8_LAS bf16x8*)(lds + PG8_SB(b, h) + boff + n * 2048 + k * 1024); } while (0)
; #define PG8_MMA(ai, bj, At, Bt) do { __builtin_amdgcn_s_setprio(1); _Pragma("unroll") for (int m = 0; m < 4; ++m) _Pragma("unroll") for (int n = 0; n < 2; ++n) _Pragma("unroll") for (int k = 0; k < 2; ++k) \
;         acc[ai][bj][m][n] = __builtin_amdgcn_mfma_f32_16x16x32_bf16(Bt[n][k], At[m][k], acc[ai][bj][m][n], 0, 0, 0); __builtin_amdgcn_s_setprio(0); } while (0)
; #define PG8_WAIT_V(n) asm volatile("s_waitcnt vmcnt(" #n ")" ::: "memory")
; #define PG8_WAIT_L(n) asm volatile("s_waitcnt lgkmcnt(" #n ")" ::: "memory")
; #define PG8_BAR __builtin_amdgcn_s_barrier()
; #define PG8_SCHED __builtin_amdgcn_sched_barrier(0)
; template <class Epi, class Sched, bool ALIGN_EPI = false, bool SP2 = false, bool ABLK = false>
; __device__ __forceinline__ void gemm_phase(PG8_LAS unsigned char* lds, const Gemm g, const Sched& S, const Epi& E) {
;     ...
;             PG8_WAIT_V(8); PG8_WAIT_L(0); PG8_BAR; PG8_MMA(1, 0, At, B0); PG8_MMA(1, 1, At, B1); PG8_BAR; PG8_SCHED;
;             PG8_LDB(B0, 1, 0); PG8_LDB(B1, 1, 1); PG8_SCHED; PG8_LDA(At, 1, 0); PG8_STAGE(PG8_SA(0, 1), a2 + hstepA, voffA);
;             PG8_WAIT_V(8); PG8_WAIT_L(0); PG8_BAR; PG8_MMA(0, 0, At, B0); PG8_MMA(0, 1, At, B1); PG8_BAR; PG8_SCHED;
.Lp4_wd_1:
	s_waitcnt lgkmcnt(0)
	s_barrier
	s_setprio 1
	s_waitcnt lgkmcnt(0)
	v_mfma_f32_16x16x32_bf16 v[60:63], v[128:131], v[204:207], 0
	v_mfma_f32_16x16x32_bf16 v[56:59], v[180:183], v[204:207], 0
	v_mfma_f32_16x16x32_bf16 v[44:47], v[128:131], v[212:215], 0
	v_mfma_f32_16x16x32_bf16 v[40:43], v[180:183], v[212:215], 0
	v_mfma_f32_16x16x32_bf16 v[28:31], v[128:131], v[220:223], 0
	v_mfma_f32_16x16x32_bf16 v[24:27], v[180:183], v[220:223], 0
	v_mfma_f32_16x16x32_bf16 v[12:15], v[128:131], v[228:231], 0
	v_mfma_f32_16x16x32_bf16 v[8:11], v[180:183], v[228:231], 0
	v_mfma_f32_16x16x32_bf16 v[60:63], v[176:179], v[208:211], v[60:63]
	v_mfma_f32_16x16x32_bf16 v[56:59], v[184:187], v[208:211], v[56:59]
	v_mfma_f32_16x16x32_bf16 v[44:47], v[176:179], v[216:219], v[44:47]
	v_mfma_f32_16x16x32_bf16 v[40:43], v[184:187], v[216:219], v[40:43]
	v_mfma_f32_16x16x32_bf16 v[28:31], v[176:179], v[224:227], v[28:31]
	v_mfma_f32_16x16x32_bf16 v[24:27], v[184:187], v[224:227], v[24:27]
	v_mfma_f32_16x16x32_bf16 v[12:15], v[176:179], v[232:235], v[12:15]
	v_mfma_f32_16x16x32_bf16 v[8:11], v[184:187], v[232:235], v[8:11]
	s_setprio 0
	s_setprio 1
	v_mfma_f32_16x16x32_bf16 v[52:55], v[188:191], v[204:207], 0
	v_mfma_f32_16x16x32_bf16 v[48:51], v[196:199], v[204:207], 0
	v_mfma_f32_16x16x32_bf16 v[36:39], v[188:191], v[212:215], 0
	v_mfma_f32_16x16x32_bf16 v[32:35], v[196:199], v[212:215], 0
	v_mfma_f32_16x16x32_bf16 v[20:23], v[188:191], v[220:223], 0
	v_mfma_f32_16x16x32_bf16 v[16:19], v[196:199], v[220:223], 0
	v_mfma_f32_16x16x32_bf16 v[4:7], v[188:191], v[228:231], 0
	v_mfma_f32_16x16x32_bf16 v[0:3], v[196:199], v[228:231], 0
	v_mfma_f32_16x16x32_bf16 v[52:55], v[192:195], v[208:211], v[52:55]
	v_mfma_f32_16x16x32_bf16 v[48:51], v[200:203], v[208:211], v[48:51]
	v_mfma_f32_16x16x32_bf16 v[36:39], v[192:195], v[216:219], v[36:39]
	v_mfma_f32_16x16x32_bf16 v[32:35], v[200:203], v[216:219], v[32:35]
	v_mfma_f32_16x16x32_bf16 v[20:23], v[192:195], v[224:227], v[20:23]
	v_mfma_f32_16x16x32_bf16 v[16:19], v[200:203], v[224:227], v[16:19]
	v_mfma_f32_16x16x32_bf16 v[4:7], v[192:195], v[232:235], v[4:7]
	v_mfma_f32_16x16x32_bf16 v[0:3], v[200:203], v[232:235], v[0:3]
	s_setprio 0
	s_barrier
	s_add_i32 s2, 0, 0x18000
	v_add_u32_e32 v171, s2, v166
	s_add_i32 s70, 0, 0x1c000
	ds_read_b128 v[128:131], v171
	ds_read_b128 v[176:179], v171 offset:1024
	ds_read_b128 v[180:183], v171 offset:2048
	ds_read_b128 v[184:187], v171 offset:3072
	v_add_u32_e32 v171, s70, v166
	ds_read_b128 v[188:191], v171
	ds_read_b128 v[192:195], v171 offset:1024
	ds_read_b128 v[196:199], v171 offset:2048
	ds_read_b128 v[200:203], v171 offset:3072
	s_add_u32 s38, s38, 0x4000
	s_addc_u32 s39, s39, 0
	s_mov_b32 m0, s44
	v_lshl_add_u64 v[238:239], s[38:39], 0, v[138:139]
	ds_read_b128 v[204:207], v168 offset:32768
	ds_read_b128 v[208:211], v168 offset:33792
	ds_read_b128 v[212:215], v168 offset:34816
	ds_read_b128 v[216:219], v168 offset:35840
	ds_read_b128 v[220:223], v168 offset:36864
	ds_read_b128 v[224:227], v168 offset:37888
	ds_read_b128 v[228:231], v168 offset:38912
	ds_read_b128 v[232:235], v168 offset:39936
	global_load_lds_dwordx4 v[238:239], off
	v_lshl_add_u64 v[238:239], s[38:39], 0, v[134:135]
	s_mov_b32 m0, s45
	s_nop 0
	global_load_lds_dwordx4 v[238:239], off
	s_waitcnt vmcnt(8)
	s_waitcnt lgkmcnt(0)
	s_barrier
	s_setprio 1
	s_waitcnt lgkmcnt(0)
	v_mfma_f32_16x16x32_bf16 v[124:127], v[128:131], v[204:207], v[124:127]
	v_mfma_f32_16x16x32_bf16 v[120:123], v[180:183], v[204:207], v[120:123]
	v_mfma_f32_16x16x32_bf16 v[108:111], v[128:131], v[212:215], v[108:111]
	v_mfma_f32_16x16x32_bf16 v[104:107], v[180:183], v[212:215], v[104:107]
	v_mfma_f32_16x16x32_bf16 v[92:95], v[128:131], v[220:223], v[92:95]
	v_mfma_f32_16x16x32_bf16 v[88:91], v[180:183], v[220:223], v[88:91]
	v_mfma_f32_16x16x32_bf16 v[76:79], v[128:131], v[228:231], v[76:79]
	v_mfma_f32_16x16x32_bf16 v[72:75], v[180:183], v[228:231], v[72:75]
	v_mfma_f32_16x16x32_bf16 v[124:127], v[176:179], v[208:211], v[124:127]
	v_mfma_f32_16x16x32_bf16 v[120:123], v[184:187], v[208:211], v[120:123]
	v_mfma_f32_16x16x32_bf16 v[108:111], v[176:179], v[216:219], v[108:111]
	v_mfma_f32_16x16x32_bf16 v[104:107], v[184:187], v[216:219], v[104:107]
	v_mfma_f32_16x16x32_bf16 v[92:95], v[176:179], v[224:227], v[92:95]
	v_mfma_f32_16x16x32_bf16 v[88:91], v[184:187], v[224:227], v[88:91]
	v_mfma_f32_16x16x32_bf16 v[76:79], v[176:179], v[232:235], v[76:79]
	v_mfma_f32_16x16x32_bf16 v[72:75], v[184:187], v[232:235], v[72:75]
	s_setprio 0
	s_setprio 1
	v_mfma_f32_16x16x32_bf16 v[116:119], v[188:191], v[204:207], v[116:119]
	v_mfma_f32_16x16x32_bf16 v[112:115], v[196:199], v[204:207], v[112:115]
	v_mfma_f32_16x16x32_bf16 v[100:103], v[188:191], v[212:215], v[100:103]
	v_mfma_f32_16x16x32_bf16 v[96:99], v[196:199], v[212:215], v[96:99]
	v_mfma_f32_16x16x32_bf16 v[84:87], v[188:191], v[220:223], v[84:87]
	v_mfma_f32_16x16x32_bf16 v[80:83], v[196:199], v[220:223], v[80:83]
	v_mfma_f32_16x16x32_bf16 v[68:71], v[188:191], v[228:231], v[68:71]
	v_mfma_f32_16x16x32_bf16 v[64:67], v[196:199], v[228:231], v[64:67]
	v_mfma_f32_16x16x32_bf16 v[116:119], v[192:195], v[208:211], v[116:119]
	v_mfma_f32_16x16x32_bf16 v[112:115], v[200:203], v[208:211], v[112:115]
	v_mfma_f32_16x16x32_bf16 v[100:103], v[192:195], v[216:219], v[100:103]
	v_mfma_f32_16x16x32_bf16 v[96:99], v[200:203], v[216:219], v[96:99]
	v_mfma_f32_16x16x32_bf16 v[84:87], v[192:195], v[224:227], v[84:87]
	v_mfma_f32_16x16x32_bf16 v[80:83], v[200:203], v[224:227], v[80:83]
	v_mfma_f32_16x16x32_bf16 v[68:71], v[192:195], v[232:235], v[68:71]
	v_mfma_f32_16x16x32_bf16 v[64:67], v[200:203], v[232:235], v[64:67]
	s_setprio 0
	s_barrier
; #define PG8_STAGE(bufoff, gbase, voff) do { _Pragma("unroll") for (int _i = 0; _i < 2; ++_i) \
;         __builtin_amdgcn_global_load_lds((const unsigned*)((const char*)(gbase) + (voff)[_i]), (PG8_LAS unsigned*)(lds + (bufoff) + ldsw + _i * 8192), 16, 0, 0); } while (0)
; #define PG8_LDA(dst, b, h) do { _Pragma("unroll") for (int m = 0; m < 4; ++m) _Pragma("unroll") for (int k = 0; k < 2; ++k) dst[m][k] = *(const PG8_LAS bf16x8*)(lds + PG8_SA(b, h) + aoff + m * 2048 + k * 1024); } while (0)
; #define PG8_MMA(ai, bj, At, Bt) do { __builtin_amdgcn_s_setprio(1); _Pragma("unroll") for (int m = 0; m < 4; ++m) _Pragma("unroll") for (int n = 0; n < 2; ++n) _Pragma("unroll") for (int k = 0; k < 2; ++k) \
;         acc[ai][bj][m][n] = __builtin_amdgcn_mfma_f32_16x16x32_bf16(Bt[n][k], At[m][k], acc[ai][bj][m][n], 0, 0, 0); __builtin_amdgcn_s_setprio(0); } while (0)
; #define PG8_WAIT_V(n) asm volatile("s_waitcnt vmcnt(" #n ")" ::: "memory")
; #define PG8_WAIT_L(n) asm volatile("s_waitcnt lgkmcnt(" #n ")" ::: "memory")
; #define PG8_BAR __builtin_amdgcn_s_barrier()
; #define PG8_SCHED __builtin_amdgcn_sched_barrier(0)
; template <class Epi, class Sched, bool ALIGN_EPI = false, bool SP2 = false, bool ABLK = false>
; __device__ __forceinline__ void gemm_phase(PG8_LAS unsigned char* lds, const Gemm g, const Sched& S, const Epi& E) {
;     ...
;             PG8_LDA(At, 1, 1); PG8_STAGE(PG8_SB(1, 0), b3, voffB); PG8_STAGE(PG8_SB(1, 1), b3 + hstep, voffB); PG8_STAGE(PG8_SA(1, 0), a3, voffA);
;             PG8_WAIT_V(8); PG8_WAIT_L(0); PG8_BAR; PG8_MMA(1, 0, At, B0); PG8_MMA(1, 1, At, B1); PG8_BAR; PG8_SCHED;
	s_add_i32 s2, s2, s3
	v_lshl_add_u64 v[172:173], v[172:173], 0, s[16:17]
	s_mov_b32 m0, s2
	ds_read_b128 v[204:207], v168 offset:49152
	ds_read_b128 v[208:211], v168 offset:50176
	ds_read_b128 v[212:215], v168 offset:51200
	ds_read_b128 v[216:219], v168 offset:52224
	ds_read_b128 v[220:223], v168 offset:53248
	ds_read_b128 v[224:227], v168 offset:54272
	ds_read_b128 v[228:231], v168 offset:55296
	ds_read_b128 v[232:235], v168 offset:56320
	global_load_lds_dwordx4 v[172:173], off
	s_add_i32 m0, s2, 0x2000
	s_add_u32 s36, s36, 0x40080
	v_lshl_add_u64 v[172:173], v[236:237], 0, s[16:17]
	s_addc_u32 s37, s37, 0
	s_add_i32 s2, s70, s3
	global_load_lds_dwordx4 v[172:173], off
	v_lshl_add_u64 v[172:173], s[36:37], 0, v[136:137]
	s_mov_b32 m0, s2
	s_nop 0
	global_load_lds_dwordx4 v[172:173], off
	v_lshl_add_u64 v[172:173], s[36:37], 0, v[132:133]
	s_add_i32 m0, s2, 0x2000
	s_nop 0
	global_load_lds_dwordx4 v[172:173], off
	v_lshl_add_u64 v[172:173], s[34:35], 0, v[138:139]
	s_mov_b32 m0, s55
	s_nop 0
	global_load_lds_dwordx4 v[172:173], off
	v_lshl_add_u64 v[172:173], s[34:35], 0, v[134:135]
	s_mov_b32 m0, s56
	s_nop 0
	global_load_lds_dwordx4 v[172:173], off
	s_waitcnt vmcnt(8)
	s_waitcnt lgkmcnt(0)
	s_barrier
	s_setprio 1
	s_waitcnt lgkmcnt(0)
	v_mfma_f32_16x16x32_bf16 v[60:63], v[128:131], v[204:207], v[60:63]
	v_mfma_f32_16x16x32_bf16 v[56:59], v[180:183], v[204:207], v[56:59]
	v_mfma_f32_16x16x32_bf16 v[44:47], v[128:131], v[212:215], v[44:47]
	v_mfma_f32_16x16x32_bf16 v[40:43], v[180:183], v[212:215], v[40:43]
	v_mfma_f32_16x16x32_bf16 v[28:31], v[128:131], v[220:223], v[28:31]
	v_mfma_f32_16x16x32_bf16 v[24:27], v[180:183], v[220:223], v[24:27]
	v_mfma_f32_16x16x32_bf16 v[12:15], v[128:131], v[228:231], v[12:15]
	v_mfma_f32_16x16x32_bf16 v[8:11], v[180:183], v[228:231], v[8:11]
	v_mfma_f32_16x16x32_bf16 v[60:63], v[176:179], v[208:211], v[60:63]
	v_mfma_f32_16x16x32_bf16 v[56:59], v[184:187], v[208:211], v[56:59]
	v_mfma_f32_16x16x32_bf16 v[44:47], v[176:179], v[216:219], v[44:47]
	v_mfma_f32_16x16x32_bf16 v[40:43], v[184:187], v[216:219], v[40:43]
	v_mfma_f32_16x16x32_bf16 v[28:31], v[176:179], v[224:227], v[28:31]
	v_mfma_f32_16x16x32_bf16 v[24:27], v[184:187], v[224:227], v[24:27]
	v_mfma_f32_16x16x32_bf16 v[12:15], v[176:179], v[232:235], v[12:15]
	v_mfma_f32_16x16x32_bf16 v[8:11], v[184:187], v[232:235], v[8:11]
	s_setprio 0
	s_setprio 1
	v_mfma_f32_16x16x32_bf16 v[52:55], v[188:191], v[204:207], v[52:55]
	v_mfma_f32_16x16x32_bf16 v[48:51], v[196:199], v[204:207], v[48:51]
	v_mfma_f32_16x16x32_bf16 v[36:39], v[188:191], v[212:215], v[36:39]
	v_mfma_f32_16x16x32_bf16 v[32:35], v[196:199], v[212:215], v[32:35]
	v_mfma_f32_16x16x32_bf16 v[20:23], v[188:191], v[220:223], v[20:23]
	v_mfma_f32_16x16x32_bf16 v[16:19], v[196:199], v[220:223], v[16:19]
	v_mfma_f32_16x16x32_bf16 v[4:7], v[188:191], v[228:231], v[4:7]
	v_mfma_f32_16x16x32_bf16 v[0:3], v[196:199], v[228:231], v[0:3]
	v_mfma_f32_16x16x32_bf16 v[52:55], v[192:195], v[208:211], v[52:55]
	v_mfma_f32_16x16x32_bf16 v[48:51], v[200:203], v[208:211], v[48:51]
	v_mfma_f32_16x16x32_bf16 v[36:39], v[192:195], v[216:219], v[36:39]
	v_mfma_f32_16x16x32_bf16 v[32:35], v[200:203], v[216:219], v[32:35]
	v_mfma_f32_16x16x32_bf16 v[20:23], v[192:195], v[224:227], v[20:23]
	v_mfma_f32_16x16x32_bf16 v[16:19], v[200:203], v[224:227], v[16:19]
	v_mfma_f32_16x16x32_bf16 v[4:7], v[192:195], v[232:235], v[4:7]
	v_mfma_f32_16x16x32_bf16 v[0:3], v[200:203], v[232:235], v[0:3]
	s_setprio 0
	s_barrier
	s_add_i32 s63, s63, 2
	s_add_u32 s61, s61, 0x100
	s_addc_u32 s62, s62, 0
	s_add_u32 s8, s8, 0x10000
	s_addc_u32 s9, s9, 0
	s_cmp_gt_u32 s63, 13
	s_cbranch_scc0 .LBB0_534
	s_branch .Lp4_kdone

; #define PG8_STAGE(bufoff, gbase, voff) do { _Pragma("unroll") for (int _i = 0; _i < 2; ++_i) \
;         __builtin_amdgcn_global_load_lds((const unsigned*)((const char*)(gbase) + (voff)[_i]), (PG8_LAS unsigned*)(lds + (bufoff) + ldsw + _i * 8192), 16, 0, 0); } while (0)
; #define PG8_LDA(dst, b, h) do { _Pragma("unroll") for (int m = 0; m < 4; ++m) _Pragma("unroll") for (int k = 0; k < 2; ++k) dst[m][k] = *(const PG8_LAS bf16x8*)(lds + PG8_SA(b, h) + aoff + m * 2048 + k * 1024); } while (0)
; #define PG8_LDB(dst, b, h) do { _Pragma("unroll") for (int n = 0; n < 2; ++n) _Pragma("unroll") for (int k = 0; k < 2; ++k) dst[n][k] = *(const PG8_LAS bf16x8*)(lds + PG8_SB(b, h) + boff + n * 2048 + k * 1024); } while (0)
; #define PG8_WAIT_V(n) asm volatile("s_waitcnt vmcnt(" #n ")" ::: "memory")
; #define PG8_WAIT_L(n) asm volatile("s_waitcnt lgkmcnt(" #n ")" ::: "memory")
; #define PG8_BAR __builtin_amdgcn_s_barrier()
; #define PG8_SCHED __builtin_amdgcn_sched_barrier(0)
; template <class Epi, class Sched, bool ALIGN_EPI = false, bool SP2 = false, bool ABLK = false>
; __device__ __forceinline__ void gemm_phase(PG8_LAS unsigned char* lds, const Gemm g, const Sched& S, const Epi& E) {
;     ...
;         const bool has_next = S.next(ui + 1, nxt);
;         const char* nA = has_next ? (const char*)g.A + (size_t)nxt.pm * tstepA : cA; const char* nB = has_next ? (const char*)g.Bt + (size_t)nxt.pn * tstep : cB;
;         for (int t = 0; t < nt; t += 2) {
;             if constexpr (Epi::MID) { if (t == nt / 2) E.mid(acc, cur, wr, wc, fr, fq); }
;             const bool last = (t == nt - 2);
;             const char* a1 = cA + (size_t)(t + 1) * kstepA;
;             const char* a2 = last ? nA : cA + (size_t)(t + 2) * kstepA; const char* b2 = last ? nB : cB + (size_t)(t + 2) * kstep;
;             const char* a3 = a2 + kstepA; const char* b3 = b2 + kstep;
;             if (last && has_next) S.a_ready(nxt);
;             if constexpr (SP2) {
;             PG8_LDB(B0, 0, 0); PG8_LDB(B1, 0, 1); PG8_SCHED; PG8_LDA(At, 0, 0); PG8_STAGE(PG8_SA(1, 1), a1 + hstepA, voffA);
;             PG8_WAIT_V(8); PG8_WAIT_L(0); PG8_BAR; PG8_MMA(0, 0, At, B0); PG8_MMA(0, 1, At, B1); PG8_BAR; PG8_SCHED;
;             PG8_LDA(At, 0, 1); PG8_STAGE(PG8_SB(0, 0), b2, voffB); PG8_STAGE(PG8_SB(0, 1), b2 + hstep, voffB); PG8_STAGE(PG8_SA(0, 0), a2, voffA);
.LBB0_577:
	s_ashr_i32 s21, s20, 31
	s_lshl_b64 s[24:25], s[20:21], 21
	s_add_u32 s24, s42, s24
	s_addc_u32 s25, s43, s25
	s_and_b64 s[28:29], s[26:27], exec
	s_cselect_b32 s21, s25, s37
	s_cselect_b32 s31, s24, s36
	s_ashr_i32 s23, s22, 31
	s_lshl_b64 s[28:29], s[22:23], 21
	s_add_u32 s28, s50, s28
	s_addc_u32 s29, s51, s29
	s_and_b64 s[38:39], s[26:27], exec
	s_cselect_b32 s23, s29, s35
	s_cselect_b32 s61, s28, s34
	s_add_u32 s62, s34, 0x100
	s_addc_u32 s63, s35, 0
	s_add_u32 s34, s36, 0xc000
	s_addc_u32 s35, s37, 0
	s_mov_b32 s64, -2
	ds_read_b128 v[142:145], v151
	ds_read_b128 v[154:157], v151 offset:1024
	ds_read_b128 v[158:161], v151 offset:2048
	ds_read_b128 v[162:165], v151 offset:3072
	ds_read_b128 v[166:169], v152
	ds_read_b128 v[170:173], v152 offset:1024
	ds_read_b128 v[174:177], v152 offset:2048
	ds_read_b128 v[178:181], v152 offset:3072
	s_add_u32 s36, s34, 0x4000
	s_addc_u32 s37, s35, 0
	s_cmp_eq_u32 s64, 60
	s_cselect_b32 s40, s31, s36
	s_cselect_b32 s41, s21, s37
	s_cselect_b32 s38, s61, s62
	s_cselect_b32 s39, s23, s63
	s_add_u32 s36, s40, 0x8000
	s_addc_u32 s37, s41, 0
	v_lshl_add_u64 v[146:147], s[34:35], 0, v[138:139]
	s_add_i32 m0, s45, 0xc000
	ds_read_b128 v[182:185], v153
	ds_read_b128 v[186:189], v153 offset:1024
	ds_read_b128 v[190:193], v153 offset:2048
	ds_read_b128 v[194:197], v153 offset:3072
	ds_read_b128 v[198:201], v153 offset:4096
	ds_read_b128 v[202:205], v153 offset:5120
	ds_read_b128 v[206:209], v153 offset:6144
	ds_read_b128 v[210:213], v153 offset:7168
	global_load_lds_dwordx4 v[146:147], off
	v_lshl_add_u64 v[146:147], s[34:35], 0, v[140:141]
	s_add_i32 m0, s45, 0xe000
	s_nop 0
	global_load_lds_dwordx4 v[146:147], off
	s_cmp_lg_u32 s100, 0x4000
	s_cbranch_scc1 .Lp5_w8_0
	s_waitcnt vmcnt(40)
	s_branch .Lp5_wd_0

; #define PG8_STAGE(bufoff, gbase, voff) do { _Pragma("unroll") for (int _i = 0; _i < 2; ++_i) \
;         __builtin_amdgcn_global_load_lds((const unsigned*)((const char*)(gbase) + (voff)[_i]), (PG8_LAS unsigned*)(lds + (bufoff) + ldsw + _i * 8192), 16, 0, 0); } while (0)
; #define PG8_LDA(dst, b, h) do { _Pragma("unroll") for (int m = 0; m < 4; ++m) _Pragma("unroll") for (int k = 0; k < 2; ++k) dst[m][k] = *(const PG8_LAS bf16x8*)(lds + PG8_SA(b, h) + aoff + m * 2048 + k * 1024); } while (0)
; #define PG8_MMA(ai, bj, At, Bt) do { __builtin_amdgcn_s_setprio(1); _Pragma("unroll") for (int m = 0; m < 4; ++m) _Pragma("unroll") for (int n = 0; n < 2; ++n) _Pragma("unroll") for (int k = 0; k < 2; ++k) \
;         acc[ai][bj][m][n] = __builtin_amdgcn_mfma_f32_16x16x32_bf16(Bt[n][k], At[m][k], acc[ai][bj][m][n], 0, 0, 0); __builtin_amdgcn_s_setprio(0); } while (0)
; #define PG8_WAIT_V(n) asm volatile("s_waitcnt vmcnt(" #n ")" ::: "memory")
; #define PG8_WAIT_L(n) asm volatile("s_waitcnt lgkmcnt(" #n ")" ::: "memory")
; #define PG8_BAR __builtin_amdgcn_s_barrier()
; #define PG8_SCHED __builtin_amdgcn_sched_barrier(0)
; template <class Epi, class Sched, bool ALIGN_EPI = false, bool SP2 = false, bool ABLK = false>
; __device__ __forceinline__ void gemm_phase(PG8_LAS unsigned char* lds, const Gemm g, const Sched& S, const Epi& E) {
;     ...
;             PG8_WAIT_V(8); PG8_WAIT_L(0); PG8_BAR; PG8_MMA(0, 0, At, B0); PG8_MMA(0, 1, At, B1); PG8_BAR; PG8_SCHED;
;             PG8_LDA(At, 0, 1); PG8_STAGE(PG8_SB(0, 0), b2, voffB); PG8_STAGE(PG8_SB(0, 1), b2 + hstep, voffB); PG8_STAGE(PG8_SA(0, 0), a2, voffA);
;             PG8_WAIT_V(8); PG8_WAIT_L(0); PG8_BAR; PG8_MMA(1, 0, At, B0); PG8_MMA(1, 1, At, B1); PG8_BAR; PG8_SCHED;
.Lp5_wd_0:
	s_waitcnt lgkmcnt(0)
	s_barrier
	s_setprio 1
	s_waitcnt lgkmcnt(0)
	v_mfma_f32_16x16x32_bf16 v[124:127], v[142:145], v[182:185], 0
	v_mfma_f32_16x16x32_bf16 v[120:123], v[158:161], v[182:185], 0
	v_mfma_f32_16x16x32_bf16 v[116:119], v[142:145], v[190:193], 0
	v_mfma_f32_16x16x32_bf16 v[112:115], v[158:161], v[190:193], 0
	v_mfma_f32_16x16x32_bf16 v[96:99], v[142:145], v[198:201], 0
	v_mfma_f32_16x16x32_bf16 v[88:91], v[158:161], v[198:201], 0
	v_mfma_f32_16x16x32_bf16 v[80:83], v[142:145], v[206:209], 0
	v_mfma_f32_16x16x32_bf16 v[72:75], v[158:161], v[206:209], 0
	v_mfma_f32_16x16x32_bf16 v[124:127], v[154:157], v[186:189], v[124:127]
	v_mfma_f32_16x16x32_bf16 v[120:123], v[162:165], v[186:189], v[120:123]
	v_mfma_f32_16x16x32_bf16 v[116:119], v[154:157], v[194:197], v[116:119]
	v_mfma_f32_16x16x32_bf16 v[112:115], v[162:165], v[194:197], v[112:115]
	v_mfma_f32_16x16x32_bf16 v[96:99], v[154:157], v[202:205], v[96:99]
	v_mfma_f32_16x16x32_bf16 v[88:91], v[162:165], v[202:205], v[88:91]
	v_mfma_f32_16x16x32_bf16 v[80:83], v[154:157], v[210:213], v[80:83]
	v_mfma_f32_16x16x32_bf16 v[72:75], v[162:165], v[210:213], v[72:75]
	s_setprio 0
	s_setprio 1
	v_mfma_f32_16x16x32_bf16 v[108:111], v[166:169], v[182:185], 0
	v_mfma_f32_16x16x32_bf16 v[104:107], v[174:177], v[182:185], 0
	v_mfma_f32_16x16x32_bf16 v[100:103], v[166:169], v[190:193], 0
	v_mfma_f32_16x16x32_bf16 v[92:95], v[174:177], v[190:193], 0
	v_mfma_f32_16x16x32_bf16 v[84:87], v[166:169], v[198:201], 0
	v_mfma_f32_16x16x32_bf16 v[76:79], v[174:177], v[198:201], 0
	v_mfma_f32_16x16x32_bf16 v[68:71], v[166:169], v[206:209], 0
	v_mfma_f32_16x16x32_bf16 v[64:67], v[174:177], v[206:209], 0
	v_mfma_f32_16x16x32_bf16 v[108:111], v[170:173], v[186:189], v[108:111]
	v_mfma_f32_16x16x32_bf16 v[104:107], v[178:181], v[186:189], v[104:107]
	v_mfma_f32_16x16x32_bf16 v[100:103], v[170:173], v[194:197], v[100:103]
	v_mfma_f32_16x16x32_bf16 v[92:95], v[178:181], v[194:197], v[92:95]
	v_mfma_f32_16x16x32_bf16 v[84:87], v[170:173], v[202:205], v[84:87]
	v_mfma_f32_16x16x32_bf16 v[76:79], v[178:181], v[202:205], v[76:79]
	v_mfma_f32_16x16x32_bf16 v[68:71], v[170:173], v[210:213], v[68:71]
	v_mfma_f32_16x16x32_bf16 v[64:67], v[178:181], v[210:213], v[64:67]
	s_setprio 0
	s_barrier
	s_add_i32 s65, s56, s44
	v_lshl_add_u64 v[146:147], s[38:39], 0, v[132:133]
	s_mov_b32 m0, s65
	ds_read_b128 v[182:185], v153 offset:16384
	ds_read_b128 v[186:189], v153 offset:17408
	ds_read_b128 v[190:193], v153 offset:18432
	ds_read_b128 v[194:197], v153 offset:19456
	ds_read_b128 v[198:201], v153 offset:20480
	ds_read_b128 v[202:205], v153 offset:21504
	ds_read_b128 v[206:209], v153 offset:22528
	ds_read_b128 v[210:213], v153 offset:23552
	global_load_lds_dwordx4 v[146:147], off
	s_add_i32 m0, s65, 0x2000
	s_add_u32 s70, s38, 0x100000
	v_lshl_add_u64 v[214:215], s[38:39], 0, v[128:129]
	s_addc_u32 s71, s39, 0
	s_add_i32 s65, s57, s44
	global_load_lds_dwordx4 v[214:215], off
	v_lshl_add_u64 v[216:217], s[70:71], 0, v[132:133]
	s_mov_b32 m0, s65
	s_nop 0
	global_load_lds_dwordx4 v[216:217], off
	v_lshl_add_u64 v[216:217], s[70:71], 0, v[128:129]
	s_add_i32 m0, s65, 0x2000
	s_nop 0
	global_load_lds_dwordx4 v[216:217], off
	v_lshl_add_u64 v[216:217], s[40:41], 0, v[134:135]
	s_mov_b32 m0, s45
	s_nop 0
	global_load_lds_dwordx4 v[216:217], off
	v_lshl_add_u64 v[216:217], s[40:41], 0, v[130:131]
	s_mov_b32 m0, s47
	s_nop 0
	global_load_lds_dwordx4 v[216:217], off
	s_cmp_lg_u32 s100, 0x4000
	s_cbranch_scc1 .Lp5_w8_1
	s_waitcnt vmcnt(40)
	s_branch .Lp5_wd_1

; #define PG8_STAGE(bufoff, gbase, voff) do { _Pragma("unroll") for (int _i = 0; _i < 2; ++_i) \
;         __builtin_amdgcn_global_load_lds((const unsigned*)((const char*)(gbase) + (voff)[_i]), (PG8_LAS unsigned*)(lds + (bufoff) + ldsw + _i * 8192), 16, 0, 0); } while (0)
; #define PG8_LDA(dst, b, h) do { _Pragma("unroll") for (int m = 0; m < 4; ++m) _Pragma("unroll") for (int k = 0; k < 2; ++k) dst[m][k] = *(const PG8_LAS bf16x8*)(lds + PG8_SA(b, h) + aoff + m * 2048 + k * 1024); } while (0)
; #define PG8_LDB(dst, b, h) do { _Pragma("unroll") for (int n = 0; n < 2; ++n) _Pragma("unroll") for (int k = 0; k < 2; ++k) dst[n][k] = *(const PG8_LAS bf16x8*)(lds + PG8_SB(b, h) + boff + n * 2048 + k * 1024); } while (0)
; #define PG8_MMA(ai, bj, At, Bt) do { __builtin_amdgcn_s_setprio(1); _Pragma("unroll") for (int m = 0; m < 4; ++m) _Pragma("unroll") for (int n = 0; n < 2; ++n) _Pragma("unroll") for (int k = 0; k < 2; ++k) \
;         acc[ai][bj][m][n] = __builtin_amdgcn_mfma_f32_16x16x32_bf16(Bt[n][k], At[m][k], acc[ai][bj][m][n], 0, 0, 0); __builtin_amdgcn_s_setprio(0); } while (0)
; #define PG8_WAIT_V(n) asm volatile("s_waitcnt vmcnt(" #n ")" ::: "memory")
; #define PG8_WAIT_L(n) asm volatile("s_waitcnt lgkmcnt(" #n ")" ::: "memory")
; #define PG8_BAR __builtin_amdgcn_s_barrier()
; #define PG8_SCHED __builtin_amdgcn_sched_barrier(0)
; template <class Epi, class Sched, bool ALIGN_EPI = false, bool SP2 = false, bool ABLK = false>
; __device__ __forceinline__ void gemm_phase(PG8_LAS unsigned char* lds, const Gemm g, const Sched& S, const Epi& E) {
;     ...
;             PG8_WAIT_V(8); PG8_WAIT_L(0); PG8_BAR; PG8_MMA(1, 0, At, B0); PG8_MMA(1, 1, At, B1); PG8_BAR; PG8_SCHED;
;             PG8_LDB(B0, 1, 0); PG8_LDB(B1, 1, 1); PG8_SCHED; PG8_LDA(At, 1, 0); PG8_STAGE(PG8_SA(0, 1), a2 + hstepA, voffA);
;             PG8_WAIT_V(8); PG8_WAIT_L(0); PG8_BAR; PG8_MMA(0, 0, At, B0); PG8_MMA(0, 1, At, B1); PG8_BAR; PG8_SCHED;
.Lp5_wd_1:
	s_waitcnt lgkmcnt(0)
	s_barrier
	s_setprio 1
	s_waitcnt lgkmcnt(0)
	v_mfma_f32_16x16x32_bf16 v[60:63], v[142:145], v[182:185], 0
	v_mfma_f32_16x16x32_bf16 v[56:59], v[158:161], v[182:185], 0
	v_mfma_f32_16x16x32_bf16 v[48:51], v[142:145], v[190:193], 0
	v_mfma_f32_16x16x32_bf16 v[40:43], v[158:161], v[190:193], 0
	v_mfma_f32_16x16x32_bf16 v[32:35], v[142:145], v[198:201], 0
	v_mfma_f32_16x16x32_bf16 v[24:27], v[158:161], v[198:201], 0
	v_mfma_f32_16x16x32_bf16 v[16:19], v[142:145], v[206:209], 0
	v_mfma_f32_16x16x32_bf16 v[8:11], v[158:161], v[206:209], 0
	v_mfma_f32_16x16x32_bf16 v[60:63], v[154:157], v[186:189], v[60:63]
	v_mfma_f32_16x16x32_bf16 v[56:59], v[162:165], v[186:189], v[56:59]
	v_mfma_f32_16x16x32_bf16 v[48:51], v[154:157], v[194:197], v[48:51]
	v_mfma_f32_16x16x32_bf16 v[40:43], v[162:165], v[194:197], v[40:43]
	v_mfma_f32_16x16x32_bf16 v[32:35], v[154:157], v[202:205], v[32:35]
	v_mfma_f32_16x16x32_bf16 v[24:27], v[162:165], v[202:205], v[24:27]
	v_mfma_f32_16x16x32_bf16 v[16:19], v[154:157], v[210:213], v[16:19]
	v_mfma_f32_16x16x32_bf16 v[8:11], v[162:165], v[210:213], v[8:11]
	s_setprio 0
	s_setprio 1
	v_mfma_f32_16x16x32_bf16 v[52:55], v[166:169], v[182:185], 0
	v_mfma_f32_16x16x32_bf16 v[44:47], v[174:177], v[182:185], 0
	v_mfma_f32_16x16x32_bf16 v[36:39], v[166:169], v[190:193], 0
	v_mfma_f32_16x16x32_bf16 v[28:31], v[174:177], v[190:193], 0
	v_mfma_f32_16x16x32_bf16 v[20:23], v[166:169], v[198:201], 0
	v_mfma_f32_16x16x32_bf16 v[12:15], v[174:177], v[198:201], 0
	v_mfma_f32_16x16x32_bf16 v[4:7], v[166:169], v[206:209], 0
	v_mfma_f32_16x16x32_bf16 v[0:3], v[174:177], v[206:209], 0
	v_mfma_f32_16x16x32_bf16 v[52:55], v[170:173], v[186:189], v[52:55]
	v_mfma_f32_16x16x32_bf16 v[44:47], v[178:181], v[186:189], v[44:47]
	v_mfma_f32_16x16x32_bf16 v[36:39], v[170:173], v[194:197], v[36:39]
	v_mfma_f32_16x16x32_bf16 v[28:31], v[178:181], v[194:197], v[28:31]
	v_mfma_f32_16x16x32_bf16 v[20:23], v[170:173], v[202:205], v[20:23]
	v_mfma_f32_16x16x32_bf16 v[12:15], v[178:181], v[202:205], v[12:15]
	v_mfma_f32_16x16x32_bf16 v[4:7], v[170:173], v[210:213], v[4:7]
	v_mfma_f32_16x16x32_bf16 v[0:3], v[178:181], v[210:213], v[0:3]
	s_setprio 0
	s_barrier
	s_add_i32 s65, 0, 0x18000
	v_add_u32_e32 v136, s65, v150
	s_add_i32 s68, 0, 0x1c000
	ds_read_b128 v[142:145], v136
	ds_read_b128 v[154:157], v136 offset:1024
	ds_read_b128 v[158:161], v136 offset:2048
	ds_read_b128 v[162:165], v136 offset:3072
	v_add_u32_e32 v136, s68, v150
	ds_read_b128 v[166:169], v136
	ds_read_b128 v[170:173], v136 offset:1024
	ds_read_b128 v[174:177], v136 offset:2048
	ds_read_b128 v[178:181], v136 offset:3072
	s_add_u32 s40, s40, 0x4000
	s_addc_u32 s41, s41, 0
	s_mov_b32 m0, s48
	v_lshl_add_u64 v[216:217], s[40:41], 0, v[134:135]
	ds_read_b128 v[182:185], v153 offset:32768
	ds_read_b128 v[186:189], v153 offset:33792
	ds_read_b128 v[190:193], v153 offset:34816
	ds_read_b128 v[194:197], v153 offset:35840
	ds_read_b128 v[198:201], v153 offset:36864
	ds_read_b128 v[202:205], v153 offset:37888
	ds_read_b128 v[206:209], v153 offset:38912
	ds_read_b128 v[210:213], v153 offset:39936
	global_load_lds_dwordx4 v[216:217], off
	v_lshl_add_u64 v[216:217], s[40:41], 0, v[130:131]
	s_mov_b32 m0, s49
	s_nop 0
	global_load_lds_dwordx4 v[216:217], off
	s_waitcnt vmcnt(8)
	s_waitcnt lgkmcnt(0)
	s_barrier
	s_setprio 1
	s_waitcnt lgkmcnt(0)
	v_mfma_f32_16x16x32_bf16 v[124:127], v[142:145], v[182:185], v[124:127]
	v_mfma_f32_16x16x32_bf16 v[120:123], v[158:161], v[182:185], v[120:123]
	v_mfma_f32_16x16x32_bf16 v[116:119], v[142:145], v[190:193], v[116:119]
	v_mfma_f32_16x16x32_bf16 v[112:115], v[158:161], v[190:193], v[112:115]
	v_mfma_f32_16x16x32_bf16 v[96:99], v[142:145], v[198:201], v[96:99]
	v_mfma_f32_16x16x32_bf16 v[88:91], v[158:161], v[198:201], v[88:91]
	v_mfma_f32_16x16x32_bf16 v[80:83], v[142:145], v[206:209], v[80:83]
	v_mfma_f32_16x16x32_bf16 v[72:75], v[158:161], v[206:209], v[72:75]
	v_mfma_f32_16x16x32_bf16 v[124:127], v[154:157], v[186:189], v[124:127]
	v_mfma_f32_16x16x32_bf16 v[120:123], v[162:165], v[186:189], v[120:123]
	v_mfma_f32_16x16x32_bf16 v[116:119], v[154:157], v[194:197], v[116:119]
	v_mfma_f32_16x16x32_bf16 v[112:115], v[162:165], v[194:197], v[112:115]
	v_mfma_f32_16x16x32_bf16 v[96:99], v[154:157], v[202:205], v[96:99]
	v_mfma_f32_16x16x32_bf16 v[88:91], v[162:165], v[202:205], v[88:91]
	v_mfma_f32_16x16x32_bf16 v[80:83], v[154:157], v[210:213], v[80:83]
	v_mfma_f32_16x16x32_bf16 v[72:75], v[162:165], v[210:213], v[72:75]
	s_setprio 0
	s_setprio 1
	v_mfma_f32_16x16x32_bf16 v[108:111], v[166:169], v[182:185], v[108:111]
	v_mfma_f32_16x16x32_bf16 v[104:107], v[174:177], v[182:185], v[104:107]
	v_mfma_f32_16x16x32_bf16 v[100:103], v[166:169], v[190:193], v[100:103]
	v_mfma_f32_16x16x32_bf16 v[92:95], v[174:177], v[190:193], v[92:95]
	v_mfma_f32_16x16x32_bf16 v[84:87], v[166:169], v[198:201], v[84:87]
	v_mfma_f32_16x16x32_bf16 v[76:79], v[174:177], v[198:201], v[76:79]
	v_mfma_f32_16x16x32_bf16 v[68:71], v[166:169], v[206:209], v[68:71]
	v_mfma_f32_16x16x32_bf16 v[64:67], v[174:177], v[206:209], v[64:67]
	v_mfma_f32_16x16x32_bf16 v[108:111], v[170:173], v[186:189], v[108:111]
	v_mfma_f32_16x16x32_bf16 v[104:107], v[178:181], v[186:189], v[104:107]
	v_mfma_f32_16x16x32_bf16 v[100:103], v[170:173], v[194:197], v[100:103]
	v_mfma_f32_16x16x32_bf16 v[92:95], v[178:181], v[194:197], v[92:95]
	v_mfma_f32_16x16x32_bf16 v[84:87], v[170:173], v[202:205], v[84:87]
	v_mfma_f32_16x16x32_bf16 v[76:79], v[178:181], v[202:205], v[76:79]
	v_mfma_f32_16x16x32_bf16 v[68:71], v[170:173], v[210:213], v[68:71]
	v_mfma_f32_16x16x32_bf16 v[64:67], v[178:181], v[210:213], v[64:67]
	s_setprio 0
	s_barrier
; #define PG8_STAGE(bufoff, gbase, voff) do { _Pragma("unroll") for (int _i = 0; _i < 2; ++_i) \
;         __builtin_amdgcn_global_load_lds((const unsigned*)((const char*)(gbase) + (voff)[_i]), (PG8_LAS unsigned*)(lds + (bufoff) + ldsw + _i * 8192), 16, 0, 0); } while (0)
; #define PG8_LDA(dst, b, h) do { _Pragma("unroll") for (int m = 0; m < 4; ++m) _Pragma("unroll") for (int k = 0; k < 2; ++k) dst[m][k] = *(const PG8_LAS bf16x8*)(lds + PG8_SA(b, h) + aoff + m * 2048 + k * 1024); } while (0)
; #define PG8_MMA(ai, bj, At, Bt) do { __builtin_amdgcn_s_setprio(1); _Pragma("unroll") for (int m = 0; m < 4; ++m) _Pragma("unroll") for (int n = 0; n < 2; ++n) _Pragma("unroll") for (int k = 0; k < 2; ++k) \
;         acc[ai][bj][m][n] = __builtin_amdgcn_mfma_f32_16x16x32_bf16(Bt[n][k], At[m][k], acc[ai][bj][m][n], 0, 0, 0); __builtin_amdgcn_s_setprio(0); } while (0)
; #define PG8_WAIT_V(n) asm volatile("s_waitcnt vmcnt(" #n ")" ::: "memory")
; #define PG8_WAIT_L(n) asm volatile("s_waitcnt lgkmcnt(" #n ")" ::: "memory")
; #define PG8_BAR __builtin_amdgcn_s_barrier()
; #define PG8_SCHED __builtin_amdgcn_sched_barrier(0)
; template <class Epi, class Sched, bool ALIGN_EPI = false, bool SP2 = false, bool ABLK = false>
; __device__ __forceinline__ void gemm_phase(PG8_LAS unsigned char* lds, const Gemm g, const Sched& S, const Epi& E) {
;     ...
;             PG8_LDA(At, 1, 1); PG8_STAGE(PG8_SB(1, 0), b3, voffB); PG8_STAGE(PG8_SB(1, 1), b3 + hstep, voffB); PG8_STAGE(PG8_SA(1, 0), a3, voffA);
;             PG8_WAIT_V(8); PG8_WAIT_L(0); PG8_BAR; PG8_MMA(1, 0, At, B0); PG8_MMA(1, 1, At, B1); PG8_BAR; PG8_SCHED;
	s_add_i32 s40, s65, s44
	v_lshl_add_u64 v[146:147], v[146:147], 0, s[4:5]
	s_mov_b32 m0, s40
	ds_read_b128 v[182:185], v153 offset:49152
	ds_read_b128 v[186:189], v153 offset:50176
	ds_read_b128 v[190:193], v153 offset:51200
	ds_read_b128 v[194:197], v153 offset:52224
	ds_read_b128 v[198:201], v153 offset:53248
	ds_read_b128 v[202:205], v153 offset:54272
	ds_read_b128 v[206:209], v153 offset:55296
	ds_read_b128 v[210:213], v153 offset:56320
	global_load_lds_dwordx4 v[146:147], off
	s_add_i32 m0, s40, 0x2000
	s_add_u32 s38, s38, 0x100080
	v_lshl_add_u64 v[146:147], v[214:215], 0, s[4:5]
	s_addc_u32 s39, s39, 0
	s_add_i32 s40, s68, s44
	global_load_lds_dwordx4 v[146:147], off
	v_lshl_add_u64 v[146:147], s[38:39], 0, v[132:133]
	s_mov_b32 m0, s40
	s_nop 0
	global_load_lds_dwordx4 v[146:147], off
	v_lshl_add_u64 v[146:147], s[38:39], 0, v[128:129]
	s_add_i32 m0, s40, 0x2000
	s_nop 0
	global_load_lds_dwordx4 v[146:147], off
	v_lshl_add_u64 v[146:147], s[36:37], 0, v[134:135]
	s_mov_b32 m0, s54
	s_nop 0
	global_load_lds_dwordx4 v[146:147], off
	v_lshl_add_u64 v[146:147], s[36:37], 0, v[130:131]
	s_mov_b32 m0, s55
	s_nop 0
	global_load_lds_dwordx4 v[146:147], off
	s_waitcnt vmcnt(8)
	s_waitcnt lgkmcnt(0)
	s_barrier
	s_setprio 1
	s_waitcnt lgkmcnt(0)
	v_mfma_f32_16x16x32_bf16 v[60:63], v[142:145], v[182:185], v[60:63]
	v_mfma_f32_16x16x32_bf16 v[56:59], v[158:161], v[182:185], v[56:59]
	v_mfma_f32_16x16x32_bf16 v[48:51], v[142:145], v[190:193], v[48:51]
	v_mfma_f32_16x16x32_bf16 v[40:43], v[158:161], v[190:193], v[40:43]
	v_mfma_f32_16x16x32_bf16 v[32:35], v[142:145], v[198:201], v[32:35]
	v_mfma_f32_16x16x32_bf16 v[24:27], v[158:161], v[198:201], v[24:27]
	v_mfma_f32_16x16x32_bf16 v[16:19], v[142:145], v[206:209], v[16:19]
	v_mfma_f32_16x16x32_bf16 v[8:11], v[158:161], v[206:209], v[8:11]
	v_mfma_f32_16x16x32_bf16 v[60:63], v[154:157], v[186:189], v[60:63]
	v_mfma_f32_16x16x32_bf16 v[56:59], v[162:165], v[186:189], v[56:59]
	v_mfma_f32_16x16x32_bf16 v[48:51], v[154:157], v[194:197], v[48:51]
	v_mfma_f32_16x16x32_bf16 v[40:43], v[162:165], v[194:197], v[40:43]
	v_mfma_f32_16x16x32_bf16 v[32:35], v[154:157], v[202:205], v[32:35]
	v_mfma_f32_16x16x32_bf16 v[24:27], v[162:165], v[202:205], v[24:27]
	v_mfma_f32_16x16x32_bf16 v[16:19], v[154:157], v[210:213], v[16:19]
	v_mfma_f32_16x16x32_bf16 v[8:11], v[162:165], v[210:213], v[8:11]
	s_setprio 0
	s_setprio 1
	v_mfma_f32_16x16x32_bf16 v[52:55], v[166:169], v[182:185], v[52:55]
	v_mfma_f32_16x16x32_bf16 v[44:47], v[174:177], v[182:185], v[44:47]
	v_mfma_f32_16x16x32_bf16 v[36:39], v[166:169], v[190:193], v[36:39]
	v_mfma_f32_16x16x32_bf16 v[28:31], v[174:177], v[190:193], v[28:31]
	v_mfma_f32_16x16x32_bf16 v[20:23], v[166:169], v[198:201], v[20:23]
	v_mfma_f32_16x16x32_bf16 v[12:15], v[174:177], v[198:201], v[12:15]
	v_mfma_f32_16x16x32_bf16 v[4:7], v[166:169], v[206:209], v[4:7]
	v_mfma_f32_16x16x32_bf16 v[0:3], v[174:177], v[206:209], v[0:3]
	v_mfma_f32_16x16x32_bf16 v[52:55], v[170:173], v[186:189], v[52:55]
	v_mfma_f32_16x16x32_bf16 v[44:47], v[178:181], v[186:189], v[44:47]
	v_mfma_f32_16x16x32_bf16 v[36:39], v[170:173], v[194:197], v[36:39]
	v_mfma_f32_16x16x32_bf16 v[28:31], v[178:181], v[194:197], v[28:31]
	v_mfma_f32_16x16x32_bf16 v[20:23], v[170:173], v[202:205], v[20:23]
	v_mfma_f32_16x16x32_bf16 v[12:15], v[178:181], v[202:205], v[12:15]
	v_mfma_f32_16x16x32_bf16 v[4:7], v[170:173], v[210:213], v[4:7]
	v_mfma_f32_16x16x32_bf16 v[0:3], v[178:181], v[210:213], v[0:3]
	s_setprio 0
	s_barrier
	s_add_i32 s64, s64, 2
	s_add_u32 s62, s62, 0x100
	s_addc_u32 s63, s63, 0
	s_add_u32 s34, s34, 0x10000
	s_addc_u32 s35, s35, 0
	s_cmp_gt_u32 s64, 61
	s_cbranch_scc0 .LBB0_578
	s_branch .Lp5_kdone
